# rmsnorm row loops: all 32 row loads issued before the first consumer, exact vmcnt waits
# baseline (speedup 1.0000x reference)
; template <bool TO_BF16>
; DI void rms_rows(const int tid, const float* src, const float* gam, bf16_t* dst, float* fdst, int G, int c) {
;     ...
;     for (int r = (c * 8 + wave) * NR; r < MTOK; r += G * 8 * NR) {
;         f32x4 v[NR][4]; float s[NR];
; #pragma unroll
;         for (int q = 0; q < NR; ++q)
; #pragma unroll
;             for (int k = 0; k < 4; ++k) v[q][k] = *(const f32x4*)(src + (size_t)(r + q) * 1024 + k * 256 + lane * 4);
; #pragma unroll
;         for (int q = 0; q < NR; ++q) { s[q] = 0.f;
; #pragma unroll
;             for (int k = 0; k < 4; ++k) s[q] += v[q][k][0] * v[q][k][0] + v[q][k][1] * v[q][k][1] + v[q][k][2] * v[q][k][2] + v[q][k][3] * v[q][k][3]; }
.LBB0_70:
	v_add_co_u32_e32 v16, vcc, 0xffff9000, v148
	s_nop 1
	v_addc_co_u32_e32 v17, vcc, -1, v149, vcc
	global_load_dwordx4 v[140:143], v[16:17], off offset:-3072
	global_load_dwordx4 v[136:139], v[16:17], off offset:-2048
	global_load_dwordx4 v[132:135], v[16:17], off offset:-1024
	global_load_dwordx4 v[128:131], v[16:17], off
	v_add_co_u32_e32 v16, vcc, 0xffffa000, v148
	s_nop 1
	v_addc_co_u32_e32 v17, vcc, -1, v149, vcc
	global_load_dwordx4 v[124:127], v[16:17], off offset:-3072
	global_load_dwordx4 v[120:123], v[16:17], off offset:-2048
	global_load_dwordx4 v[116:119], v[16:17], off offset:-1024
	global_load_dwordx4 v[112:115], v[16:17], off
	v_add_co_u32_e32 v16, vcc, 0xffffb000, v148
	s_nop 1
	v_addc_co_u32_e32 v17, vcc, -1, v149, vcc
	global_load_dwordx4 v[108:111], v[16:17], off offset:-3072
	global_load_dwordx4 v[104:107], v[16:17], off offset:-2048
	global_load_dwordx4 v[100:103], v[16:17], off offset:-1024
	global_load_dwordx4 v[96:99], v[16:17], off
	v_add_co_u32_e32 v16, vcc, 0xffffc000, v148
	s_nop 1
	v_addc_co_u32_e32 v17, vcc, -1, v149, vcc
	global_load_dwordx4 v[92:95], v[16:17], off offset:-3072
	global_load_dwordx4 v[88:91], v[16:17], off offset:-2048
	global_load_dwordx4 v[84:87], v[16:17], off offset:-1024
	global_load_dwordx4 v[80:83], v[16:17], off
	v_add_co_u32_e32 v16, vcc, 0xffffd000, v148
	s_nop 1
	v_addc_co_u32_e32 v17, vcc, -1, v149, vcc
	global_load_dwordx4 v[76:79], v[16:17], off offset:-3072
	global_load_dwordx4 v[56:59], v[16:17], off offset:-2048
	global_load_dwordx4 v[52:55], v[16:17], off offset:-1024
	global_load_dwordx4 v[48:51], v[16:17], off
	v_add_co_u32_e32 v16, vcc, 0xffffe000, v148
	s_nop 1
	v_addc_co_u32_e32 v17, vcc, -1, v149, vcc
	global_load_dwordx4 v[44:47], v[16:17], off offset:-3072
	global_load_dwordx4 v[40:43], v[16:17], off offset:-2048
	global_load_dwordx4 v[36:39], v[16:17], off offset:-1024
	global_load_dwordx4 v[32:35], v[16:17], off
	v_add_co_u32_e32 v16, vcc, 0xfffff000, v148
	s_nop 1
	v_addc_co_u32_e32 v17, vcc, -1, v149, vcc
	global_load_dwordx4 v[28:31], v[16:17], off offset:-3072
	global_load_dwordx4 v[24:27], v[16:17], off offset:-2048
	global_load_dwordx4 v[20:23], v[16:17], off offset:-1024
	global_load_dwordx4 v[16:19], v[148:149], off offset:-4096
	global_load_dwordx4 v[72:75], v[148:149], off offset:-3072
	global_load_dwordx4 v[68:71], v[148:149], off offset:-2048
	global_load_dwordx4 v[64:67], v[148:149], off offset:-1024
	global_load_dwordx4 v[60:63], v[148:149], off
	v_add_u32_e32 v144, s66, v144
	s_waitcnt vmcnt(31)
	v_mov_b32_e32 v152, v141
	s_waitcnt vmcnt(30)
	v_mov_b32_e32 v153, v137
	v_mov_b32_e32 v150, v140
	v_mov_b32_e32 v151, v136
	v_pk_mul_f32 v[152:153], v[152:153], v[152:153]
	s_nop 0
	v_pk_fma_f32 v[150:151], v[150:151], v[150:151], v[152:153]
	v_mov_b32_e32 v152, v142
	v_mov_b32_e32 v153, v138
	v_pk_fma_f32 v[150:151], v[152:153], v[152:153], v[150:151]
	v_mov_b32_e32 v152, v143
	v_mov_b32_e32 v153, v139
	v_pk_fma_f32 v[174:175], v[152:153], v[152:153], v[150:151]
	s_waitcnt vmcnt(29)
	v_mov_b32_e32 v152, v133
	s_waitcnt vmcnt(28)
	v_mov_b32_e32 v153, v129
	v_mov_b32_e32 v150, v132
	v_mov_b32_e32 v151, v128
	v_pk_mul_f32 v[152:153], v[152:153], v[152:153]
	v_lshl_add_u64 v[148:149], v[148:149], 0, s[62:63]
	v_pk_fma_f32 v[150:151], v[150:151], v[150:151], v[152:153]
	v_mov_b32_e32 v152, v134
	v_mov_b32_e32 v153, v130
	v_pk_fma_f32 v[150:151], v[152:153], v[152:153], v[150:151]
	v_mov_b32_e32 v152, v135
	v_mov_b32_e32 v153, v131
	v_pk_fma_f32 v[176:177], v[152:153], v[152:153], v[150:151]
	s_waitcnt vmcnt(27)
	v_mov_b32_e32 v152, v125
	s_waitcnt vmcnt(26)
	v_mov_b32_e32 v153, v121
	v_mov_b32_e32 v150, v124
	v_mov_b32_e32 v151, v120
	v_pk_mul_f32 v[152:153], v[152:153], v[152:153]
	s_waitcnt vmcnt(5)
	v_mov_b32_e32 v154, v21
	v_pk_fma_f32 v[150:151], v[150:151], v[150:151], v[152:153]
	v_mov_b32_e32 v152, v126
	v_mov_b32_e32 v153, v122
	v_pk_fma_f32 v[150:151], v[152:153], v[152:153], v[150:151]
	v_mov_b32_e32 v152, v127
	v_mov_b32_e32 v153, v123
	v_pk_fma_f32 v[186:187], v[152:153], v[152:153], v[150:151]
	v_mov_b32_e32 v152, v117
	v_mov_b32_e32 v153, v113
	v_mov_b32_e32 v150, v116
	v_mov_b32_e32 v151, v112
	v_pk_mul_f32 v[152:153], v[152:153], v[152:153]
	s_waitcnt vmcnt(4)
	v_mov_b32_e32 v155, v17
	v_pk_fma_f32 v[150:151], v[150:151], v[150:151], v[152:153]
	v_mov_b32_e32 v152, v118
	v_mov_b32_e32 v153, v114
	v_pk_fma_f32 v[150:151], v[152:153], v[152:153], v[150:151]
	v_mov_b32_e32 v152, v119
	v_mov_b32_e32 v153, v115
	v_pk_fma_f32 v[188:189], v[152:153], v[152:153], v[150:151]
	v_mov_b32_e32 v152, v109
	v_mov_b32_e32 v153, v105
	v_mov_b32_e32 v150, v108
	v_mov_b32_e32 v151, v104
	v_pk_mul_f32 v[152:153], v[152:153], v[152:153]
	v_pk_mul_f32 v[154:155], v[154:155], v[154:155]
	v_pk_fma_f32 v[150:151], v[150:151], v[150:151], v[152:153]
	v_mov_b32_e32 v152, v110
	v_mov_b32_e32 v153, v106
	v_pk_fma_f32 v[150:151], v[152:153], v[152:153], v[150:151]
	v_mov_b32_e32 v152, v111
	v_mov_b32_e32 v153, v107
	v_pk_fma_f32 v[166:167], v[152:153], v[152:153], v[150:151]
	v_mov_b32_e32 v152, v101
	v_mov_b32_e32 v153, v97
	v_mov_b32_e32 v150, v100
	v_mov_b32_e32 v151, v96
	v_pk_mul_f32 v[152:153], v[152:153], v[152:153]
	s_waitcnt vmcnt(3)
	v_mov_b32_e32 v156, v73
	v_pk_fma_f32 v[150:151], v[150:151], v[150:151], v[152:153]
	v_mov_b32_e32 v152, v102
	v_mov_b32_e32 v153, v98
	v_pk_fma_f32 v[150:151], v[152:153], v[152:153], v[150:151]
	v_mov_b32_e32 v152, v103
	v_mov_b32_e32 v153, v99
	v_pk_fma_f32 v[168:169], v[152:153], v[152:153], v[150:151]
	v_mov_b32_e32 v152, v93
	v_mov_b32_e32 v153, v89
	v_mov_b32_e32 v150, v92
	v_mov_b32_e32 v151, v88
	v_pk_mul_f32 v[152:153], v[152:153], v[152:153]
	s_waitcnt vmcnt(2)
; template <bool TO_BF16>
; DI void rms_rows(const int tid, const float* src, const float* gam, bf16_t* dst, float* fdst, int G, int c) {
;     ...
;         for (int q = 0; q < NR; ++q) { s[q] = 0.f;
; #pragma unroll
;             for (int k = 0; k < 4; ++k) s[q] += v[q][k][0] * v[q][k][0] + v[q][k][1] * v[q][k][1] + v[q][k][2] * v[q][k][2] + v[q][k][3] * v[q][k][3]; }
; #pragma unroll
;         for (int o = 32; o > 0; o >>= 1)
; #pragma unroll
;             for (int q = 0; q < NR; ++q) s[q] += __shfl_xor(s[q], o);
	v_mov_b32_e32 v157, v69
	v_pk_fma_f32 v[150:151], v[150:151], v[150:151], v[152:153]
	v_mov_b32_e32 v152, v94
	v_mov_b32_e32 v153, v90
	v_pk_fma_f32 v[150:151], v[152:153], v[152:153], v[150:151]
	v_mov_b32_e32 v152, v95
	v_mov_b32_e32 v153, v91
	v_pk_fma_f32 v[170:171], v[152:153], v[152:153], v[150:151]
	v_mov_b32_e32 v152, v85
	v_mov_b32_e32 v153, v81
	v_mov_b32_e32 v150, v84
	v_mov_b32_e32 v151, v80
	v_pk_mul_f32 v[152:153], v[152:153], v[152:153]
	v_pk_mul_f32 v[156:157], v[156:157], v[156:157]
	v_pk_fma_f32 v[150:151], v[150:151], v[150:151], v[152:153]
	v_mov_b32_e32 v152, v86
	v_mov_b32_e32 v153, v82
	v_pk_fma_f32 v[150:151], v[152:153], v[152:153], v[150:151]
	v_mov_b32_e32 v152, v87
	v_mov_b32_e32 v153, v83
	v_pk_fma_f32 v[172:173], v[152:153], v[152:153], v[150:151]
	v_mov_b32_e32 v152, v77
	v_mov_b32_e32 v153, v57
	v_mov_b32_e32 v150, v76
	v_mov_b32_e32 v151, v56
	v_pk_mul_f32 v[152:153], v[152:153], v[152:153]
	s_waitcnt vmcnt(1)
	v_mov_b32_e32 v190, v65
	v_pk_fma_f32 v[150:151], v[150:151], v[150:151], v[152:153]
	v_mov_b32_e32 v152, v78
	v_mov_b32_e32 v153, v58
	v_pk_fma_f32 v[150:151], v[152:153], v[152:153], v[150:151]
	v_mov_b32_e32 v152, v79
	v_mov_b32_e32 v153, v59
	v_pk_fma_f32 v[158:159], v[152:153], v[152:153], v[150:151]
	v_mov_b32_e32 v152, v53
	v_mov_b32_e32 v153, v49
	v_mov_b32_e32 v150, v52
	v_mov_b32_e32 v151, v48
	v_pk_mul_f32 v[152:153], v[152:153], v[152:153]
	s_waitcnt vmcnt(0)
	v_mov_b32_e32 v191, v61
	v_pk_fma_f32 v[150:151], v[150:151], v[150:151], v[152:153]
	v_mov_b32_e32 v152, v54
	v_mov_b32_e32 v153, v50
	v_pk_fma_f32 v[150:151], v[152:153], v[152:153], v[150:151]
	v_mov_b32_e32 v152, v55
	v_mov_b32_e32 v153, v51
	v_pk_fma_f32 v[160:161], v[152:153], v[152:153], v[150:151]
	v_mov_b32_e32 v152, v45
	v_mov_b32_e32 v153, v41
	v_mov_b32_e32 v150, v44
	v_mov_b32_e32 v151, v40
	v_pk_mul_f32 v[152:153], v[152:153], v[152:153]
	v_pk_mul_f32 v[190:191], v[190:191], v[190:191]
	v_pk_fma_f32 v[150:151], v[150:151], v[150:151], v[152:153]
	v_mov_b32_e32 v152, v46
	v_mov_b32_e32 v153, v42
	v_pk_fma_f32 v[150:151], v[152:153], v[152:153], v[150:151]
	v_mov_b32_e32 v152, v47
	v_mov_b32_e32 v153, v43
	v_pk_fma_f32 v[162:163], v[152:153], v[152:153], v[150:151]
	v_mov_b32_e32 v152, v37
	v_mov_b32_e32 v153, v33
	v_mov_b32_e32 v150, v36
	v_mov_b32_e32 v151, v32
	v_pk_mul_f32 v[152:153], v[152:153], v[152:153]
	s_nop 0
	v_pk_fma_f32 v[150:151], v[150:151], v[150:151], v[152:153]
	v_mov_b32_e32 v152, v38
	v_mov_b32_e32 v153, v34
	v_pk_fma_f32 v[150:151], v[152:153], v[152:153], v[150:151]
	v_mov_b32_e32 v152, v39
	v_mov_b32_e32 v153, v35
	v_pk_fma_f32 v[164:165], v[152:153], v[152:153], v[150:151]
	v_mov_b32_e32 v152, v29
	v_mov_b32_e32 v153, v25
	v_mov_b32_e32 v150, v28
	v_mov_b32_e32 v151, v24
	v_pk_mul_f32 v[152:153], v[152:153], v[152:153]
	s_nop 0
	v_pk_fma_f32 v[150:151], v[150:151], v[150:151], v[152:153]
	v_mov_b32_e32 v152, v30
	v_mov_b32_e32 v153, v26
	v_pk_fma_f32 v[150:151], v[152:153], v[152:153], v[150:151]
	v_mov_b32_e32 v152, v31
	v_mov_b32_e32 v153, v27
	v_pk_fma_f32 v[150:151], v[152:153], v[152:153], v[150:151]
	v_mov_b32_e32 v152, v20
	v_mov_b32_e32 v153, v16
	v_pk_fma_f32 v[152:153], v[152:153], v[152:153], v[154:155]
	v_mov_b32_e32 v154, v22
	v_mov_b32_e32 v155, v18
	v_pk_fma_f32 v[152:153], v[154:155], v[154:155], v[152:153]
	v_mov_b32_e32 v154, v23
	v_mov_b32_e32 v155, v19
	v_pk_fma_f32 v[152:153], v[154:155], v[154:155], v[152:153]
	v_mov_b32_e32 v154, v72
	v_mov_b32_e32 v155, v68
	v_pk_fma_f32 v[154:155], v[154:155], v[154:155], v[156:157]
	v_mov_b32_e32 v156, v74
	v_mov_b32_e32 v157, v70
	v_pk_fma_f32 v[154:155], v[156:157], v[156:157], v[154:155]
	v_mov_b32_e32 v156, v75
	v_mov_b32_e32 v157, v71
	v_pk_fma_f32 v[154:155], v[156:157], v[156:157], v[154:155]
	v_mov_b32_e32 v156, v64
	v_mov_b32_e32 v157, v60
	v_pk_fma_f32 v[156:157], v[156:157], v[156:157], v[190:191]
	v_mov_b32_e32 v190, v66
	v_mov_b32_e32 v191, v62
	v_pk_fma_f32 v[156:157], v[190:191], v[190:191], v[156:157]
	v_mov_b32_e32 v190, v67
	v_mov_b32_e32 v191, v63
	v_pk_fma_f32 v[156:157], v[190:191], v[190:191], v[156:157]
	v_mov_b32_e32 v190, v186
	v_mov_b32_e32 v191, v174
	v_mov_b32_e32 v174, v187
	v_pk_add_f32 v[174:175], v[190:191], v[174:175]
	v_mov_b32_e32 v186, v188
	v_mov_b32_e32 v187, v176
	v_pk_add_f32 v[174:175], v[174:175], v[186:187]
	v_mov_b32_e32 v176, v189
	v_pk_add_f32 v[174:175], v[174:175], v[176:177]
	ds_bpermute_b32 v177, v178, v175
	ds_bpermute_b32 v176, v178, v174
	s_waitcnt lgkmcnt(0)
	v_pk_add_f32 v[174:175], v[174:175], v[176:177]
	ds_bpermute_b32 v177, v179, v175
	ds_bpermute_b32 v176, v179, v174
	s_waitcnt lgkmcnt(0)
	v_pk_add_f32 v[174:175], v[174:175], v[176:177]
	ds_bpermute_b32 v177, v180, v175
	ds_bpermute_b32 v176, v180, v174
	s_waitcnt lgkmcnt(0)
	v_pk_add_f32 v[174:175], v[174:175], v[176:177]
	ds_bpermute_b32 v177, v183, v175
	ds_bpermute_b32 v176, v183, v174
	s_waitcnt lgkmcnt(0)
	v_pk_add_f32 v[174:175], v[174:175], v[176:177]
	ds_bpermute_b32 v177, v184, v175
	ds_bpermute_b32 v176, v184, v174
	s_waitcnt lgkmcnt(0)
	v_pk_add_f32 v[174:175], v[174:175], v[176:177]
	ds_bpermute_b32 v177, v185, v175
	ds_bpermute_b32 v176, v185, v174
	s_waitcnt lgkmcnt(0)
; template <bool TO_BF16>
; DI void rms_rows(const int tid, const float* src, const float* gam, bf16_t* dst, float* fdst, int G, int c) {
;     ...
;             for (int q = 0; q < NR; ++q) s[q] += __shfl_xor(s[q], o);
; #pragma unroll
;         for (int q = 0; q < NR; ++q) { const float sc = rsqrtf(s[q] * (1.f / 1024.f) + 1e-6f);
; #pragma unroll
;             for (int k = 0; k < 4; ++k) {
;                 if (TO_BF16) { u32x2 o; o.x = pk2(v[q][k][0] * sc * g4[k][0], v[q][k][1] * sc * g4[k][1]); o.y = pk2(v[q][k][2] * sc * g4[k][2], v[q][k][3] * sc * g4[k][3]);
;                     *(u32x2*)(dst + (size_t)(r + q) * 1024 + k * 256 + lane * 4) = o; }
	v_pk_add_f32 v[176:177], v[174:175], v[176:177]
	v_mov_b64_e32 v[174:175], s[26:27]
	v_pk_fma_f32 v[176:177], v[176:177], s[2:3], v[174:175] op_sel_hi:[1,0,0]
	s_nop 0
	v_mul_f32_e32 v145, 0x4b800000, v177
	v_cmp_gt_f32_e64 s[0:1], s3, v177
	v_cmp_gt_f32_e32 vcc, s3, v176
	s_nop 0
	v_cndmask_b32_e64 v145, v177, v145, s[0:1]
	v_rsq_f32_e32 v145, v145
	s_nop 0
	v_mul_f32_e32 v177, 0x45800000, v145
	v_cndmask_b32_e64 v186, v145, v177, s[0:1]
	v_pk_mul_f32 v[140:141], v[140:141], v[186:187] op_sel_hi:[1,0]
	v_pk_mul_f32 v[142:143], v[142:143], v[186:187] op_sel_hi:[1,0]
	v_pk_mul_f32 v[140:141], v[12:13], v[140:141]
	v_pk_mul_f32 v[142:143], v[14:15], v[142:143]
	v_pk_mul_f32 v[128:129], v[128:129], v[186:187] op_sel_hi:[1,0]
	v_pk_mul_f32 v[130:131], v[130:131], v[186:187] op_sel_hi:[1,0]
	v_cvt_pk_bf16_f32 v140, v140, v141
	v_cvt_pk_bf16_f32 v141, v142, v143
	v_add_co_u32_e64 v142, s[0:1], s18, v146
	v_pk_mul_f32 v[128:129], v[0:1], v[128:129]
	v_pk_mul_f32 v[130:131], v[2:3], v[130:131]
	v_addc_co_u32_e64 v143, s[0:1], -1, v147, s[0:1]
	v_cvt_pk_bf16_f32 v128, v128, v129
	v_cvt_pk_bf16_f32 v129, v130, v131
	global_store_dwordx2 v[142:143], v[128:129], off offset:-2048
	v_mul_f32_e32 v128, 0x4b800000, v176
	v_cndmask_b32_e32 v128, v176, v128, vcc
	v_rsq_f32_e32 v128, v128
	v_pk_mul_f32 v[136:137], v[136:137], v[186:187] op_sel_hi:[1,0]
	v_pk_mul_f32 v[138:139], v[138:139], v[186:187] op_sel_hi:[1,0]
	v_pk_mul_f32 v[132:133], v[132:133], v[186:187] op_sel_hi:[1,0]
	v_mul_f32_e32 v129, 0x45800000, v128
	v_cndmask_b32_e32 v128, v128, v129, vcc
	v_pk_mul_f32 v[112:113], v[112:113], v[128:129] op_sel_hi:[1,0]
	v_pk_mul_f32 v[114:115], v[114:115], v[128:129] op_sel_hi:[1,0]
	v_pk_mul_f32 v[112:113], v[0:1], v[112:113]
	v_pk_mul_f32 v[114:115], v[2:3], v[114:115]
	v_pk_mul_f32 v[116:117], v[116:117], v[128:129] op_sel_hi:[1,0]
	v_pk_mul_f32 v[118:119], v[118:119], v[128:129] op_sel_hi:[1,0]
	v_cvt_pk_bf16_f32 v112, v112, v113
	v_cvt_pk_bf16_f32 v113, v114, v115
	v_add_co_u32_e32 v114, vcc, s24, v146
	v_pk_mul_f32 v[116:117], v[4:5], v[116:117]
	v_pk_mul_f32 v[118:119], v[6:7], v[118:119]
	v_addc_co_u32_e32 v115, vcc, -1, v147, vcc
	v_cvt_pk_bf16_f32 v116, v116, v117
	v_cvt_pk_bf16_f32 v117, v118, v119
	global_store_dwordx2 v[114:115], v[112:113], off offset:-4096
	v_mov_b32_e32 v112, v170
	v_mov_b32_e32 v113, v166
	v_mov_b32_e32 v166, v171
	global_store_dwordx2 v[142:143], v[116:117], off offset:-512
	v_pk_add_f32 v[112:113], v[112:113], v[166:167]
	v_mov_b32_e32 v116, v172
	v_mov_b32_e32 v117, v168
	v_pk_add_f32 v[112:113], v[112:113], v[116:117]
	v_mov_b32_e32 v168, v173
	v_pk_add_f32 v[112:113], v[112:113], v[168:169]
	ds_bpermute_b32 v117, v178, v113
	ds_bpermute_b32 v116, v178, v112
	v_pk_mul_f32 v[134:135], v[134:135], v[186:187] op_sel_hi:[1,0]
	v_pk_mul_f32 v[124:125], v[124:125], v[128:129] op_sel_hi:[1,0]
	v_pk_mul_f32 v[126:127], v[126:127], v[128:129] op_sel_hi:[1,0]
	v_pk_mul_f32 v[120:121], v[120:121], v[128:129] op_sel_hi:[1,0]
	s_waitcnt lgkmcnt(0)
	v_pk_add_f32 v[112:113], v[112:113], v[116:117]
	ds_bpermute_b32 v117, v179, v113
	ds_bpermute_b32 v116, v179, v112
	v_pk_mul_f32 v[122:123], v[122:123], v[128:129] op_sel_hi:[1,0]
	v_pk_mul_f32 v[136:137], v[8:9], v[136:137]
	v_pk_mul_f32 v[138:139], v[10:11], v[138:139]
	v_pk_mul_f32 v[132:133], v[4:5], v[132:133]
	s_waitcnt lgkmcnt(0)
	v_pk_add_f32 v[112:113], v[112:113], v[116:117]
	ds_bpermute_b32 v117, v180, v113
	ds_bpermute_b32 v116, v180, v112
	v_pk_mul_f32 v[134:135], v[6:7], v[134:135]
	v_pk_mul_f32 v[124:125], v[12:13], v[124:125]
	v_pk_mul_f32 v[126:127], v[14:15], v[126:127]
	v_pk_mul_f32 v[120:121], v[8:9], v[120:121]
	s_waitcnt lgkmcnt(0)
	v_pk_add_f32 v[112:113], v[112:113], v[116:117]
	ds_bpermute_b32 v117, v183, v113
	ds_bpermute_b32 v116, v183, v112
	v_pk_mul_f32 v[122:123], v[10:11], v[122:123]
	v_cvt_pk_bf16_f32 v136, v136, v137
	v_cvt_pk_bf16_f32 v137, v138, v139
	v_cvt_pk_bf16_f32 v132, v132, v133
	s_waitcnt lgkmcnt(0)
	v_pk_add_f32 v[112:113], v[112:113], v[116:117]
	ds_bpermute_b32 v117, v184, v113
	ds_bpermute_b32 v116, v184, v112
	v_cvt_pk_bf16_f32 v133, v134, v135
	v_cvt_pk_bf16_f32 v124, v124, v125
	v_cvt_pk_bf16_f32 v125, v126, v127
	v_cvt_pk_bf16_f32 v120, v120, v121
	s_waitcnt lgkmcnt(0)
	v_pk_add_f32 v[112:113], v[112:113], v[116:117]
	ds_bpermute_b32 v117, v185, v113
	ds_bpermute_b32 v116, v185, v112
	v_cvt_pk_bf16_f32 v121, v122, v123
	global_store_dwordx2 v[142:143], v[140:141], off offset:-3584
	global_store_dwordx2 v[142:143], v[136:137], off offset:-3072
	global_store_dwordx2 v[142:143], v[132:133], off offset:-2560
	s_waitcnt lgkmcnt(0)
; template <bool TO_BF16>
; DI void rms_rows(const int tid, const float* src, const float* gam, bf16_t* dst, float* fdst, int G, int c) {
;     ...
;         for (int o = 32; o > 0; o >>= 1)
; #pragma unroll
;             for (int q = 0; q < NR; ++q) s[q] += __shfl_xor(s[q], o);
; #pragma unroll
;         for (int q = 0; q < NR; ++q) { const float sc = rsqrtf(s[q] * (1.f / 1024.f) + 1e-6f);
; #pragma unroll
;             for (int k = 0; k < 4; ++k) {
;                 if (TO_BF16) { u32x2 o; o.x = pk2(v[q][k][0] * sc * g4[k][0], v[q][k][1] * sc * g4[k][1]); o.y = pk2(v[q][k][2] * sc * g4[k][2], v[q][k][3] * sc * g4[k][3]);
;                     *(u32x2*)(dst + (size_t)(r + q) * 1024 + k * 256 + lane * 4) = o; }
;                 else *(f32x4*)(fdst + (size_t)(r + q) * 1024 + k * 256 + lane * 4) = v[q][k] * sc * g4[k]; } }
	v_pk_add_f32 v[112:113], v[112:113], v[116:117]
	global_store_dwordx2 v[142:143], v[124:125], off offset:-1536
	v_pk_fma_f32 v[112:113], v[112:113], s[2:3], v[174:175] op_sel_hi:[1,0,0]
	global_store_dwordx2 v[142:143], v[120:121], off offset:-1024
	v_mul_f32_e32 v116, 0x4b800000, v113
	v_cmp_gt_f32_e64 s[0:1], s3, v113
	v_cmp_gt_f32_e32 vcc, s3, v112
	s_nop 0
	v_cndmask_b32_e64 v113, v113, v116, s[0:1]
	v_rsq_f32_e32 v113, v113
	s_nop 0
	v_mul_f32_e32 v116, 0x45800000, v113
	v_cndmask_b32_e64 v116, v113, v116, s[0:1]
	v_pk_mul_f32 v[96:97], v[96:97], v[116:117] op_sel_hi:[1,0]
	v_pk_mul_f32 v[98:99], v[98:99], v[116:117] op_sel_hi:[1,0]
	v_pk_mul_f32 v[96:97], v[0:1], v[96:97]
	v_pk_mul_f32 v[98:99], v[2:3], v[98:99]
	v_cvt_pk_bf16_f32 v96, v96, v97
	v_cvt_pk_bf16_f32 v97, v98, v99
	global_store_dwordx2 v[114:115], v[96:97], off offset:-2048
	v_mul_f32_e32 v96, 0x4b800000, v112
	v_cndmask_b32_e32 v96, v112, v96, vcc
	v_rsq_f32_e32 v96, v96
	v_pk_mul_f32 v[108:109], v[108:109], v[116:117] op_sel_hi:[1,0]
	v_pk_mul_f32 v[110:111], v[110:111], v[116:117] op_sel_hi:[1,0]
	v_pk_mul_f32 v[104:105], v[104:105], v[116:117] op_sel_hi:[1,0]
	v_mul_f32_e32 v97, 0x45800000, v96
	v_cndmask_b32_e32 v96, v96, v97, vcc
	v_pk_mul_f32 v[80:81], v[80:81], v[96:97] op_sel_hi:[1,0]
	v_pk_mul_f32 v[82:83], v[82:83], v[96:97] op_sel_hi:[1,0]
	v_pk_mul_f32 v[80:81], v[0:1], v[80:81]
	v_pk_mul_f32 v[82:83], v[2:3], v[82:83]
	v_cvt_pk_bf16_f32 v80, v80, v81
	v_cvt_pk_bf16_f32 v81, v82, v83
	global_store_dwordx2 v[114:115], v[80:81], off
	v_mov_b32_e32 v80, v162
	v_mov_b32_e32 v81, v158
	v_mov_b32_e32 v158, v163
	v_pk_add_f32 v[80:81], v[80:81], v[158:159]
	v_mov_b32_e32 v82, v164
	v_mov_b32_e32 v83, v160
	v_pk_add_f32 v[80:81], v[80:81], v[82:83]
	v_mov_b32_e32 v160, v165
	v_pk_add_f32 v[80:81], v[80:81], v[160:161]
	ds_bpermute_b32 v83, v178, v81
	ds_bpermute_b32 v82, v178, v80
	v_pk_mul_f32 v[106:107], v[106:107], v[116:117] op_sel_hi:[1,0]
	v_pk_mul_f32 v[100:101], v[100:101], v[116:117] op_sel_hi:[1,0]
	v_pk_mul_f32 v[102:103], v[102:103], v[116:117] op_sel_hi:[1,0]
	v_pk_mul_f32 v[92:93], v[92:93], v[96:97] op_sel_hi:[1,0]
	s_waitcnt lgkmcnt(0)
	v_pk_add_f32 v[80:81], v[80:81], v[82:83]
	ds_bpermute_b32 v83, v179, v81
	ds_bpermute_b32 v82, v179, v80
	v_pk_mul_f32 v[94:95], v[94:95], v[96:97] op_sel_hi:[1,0]
	v_pk_mul_f32 v[88:89], v[88:89], v[96:97] op_sel_hi:[1,0]
	v_pk_mul_f32 v[90:91], v[90:91], v[96:97] op_sel_hi:[1,0]
	v_pk_mul_f32 v[84:85], v[84:85], v[96:97] op_sel_hi:[1,0]
	s_waitcnt lgkmcnt(0)
	v_pk_add_f32 v[80:81], v[80:81], v[82:83]
	ds_bpermute_b32 v83, v180, v81
	ds_bpermute_b32 v82, v180, v80
	v_pk_mul_f32 v[86:87], v[86:87], v[96:97] op_sel_hi:[1,0]
	v_pk_mul_f32 v[108:109], v[12:13], v[108:109]
	v_pk_mul_f32 v[110:111], v[14:15], v[110:111]
	v_pk_mul_f32 v[104:105], v[8:9], v[104:105]
	s_waitcnt lgkmcnt(0)
	v_pk_add_f32 v[80:81], v[80:81], v[82:83]
	ds_bpermute_b32 v83, v183, v81
	ds_bpermute_b32 v82, v183, v80
	v_pk_mul_f32 v[106:107], v[10:11], v[106:107]
	v_pk_mul_f32 v[100:101], v[4:5], v[100:101]
	v_pk_mul_f32 v[102:103], v[6:7], v[102:103]
	v_pk_mul_f32 v[92:93], v[12:13], v[92:93]
	s_waitcnt lgkmcnt(0)
	v_pk_add_f32 v[80:81], v[80:81], v[82:83]
	ds_bpermute_b32 v83, v184, v81
	ds_bpermute_b32 v82, v184, v80
	v_pk_mul_f32 v[94:95], v[14:15], v[94:95]
	v_pk_mul_f32 v[88:89], v[8:9], v[88:89]
	v_pk_mul_f32 v[90:91], v[10:11], v[90:91]
	v_pk_mul_f32 v[84:85], v[4:5], v[84:85]
	s_waitcnt lgkmcnt(0)
	v_pk_add_f32 v[80:81], v[80:81], v[82:83]
	ds_bpermute_b32 v83, v185, v81
	ds_bpermute_b32 v82, v185, v80
	v_pk_mul_f32 v[86:87], v[6:7], v[86:87]
	v_cvt_pk_bf16_f32 v108, v108, v109
	v_cvt_pk_bf16_f32 v109, v110, v111
	v_cvt_pk_bf16_f32 v104, v104, v105
	s_waitcnt lgkmcnt(0)
	v_pk_add_f32 v[80:81], v[80:81], v[82:83]
	v_cvt_pk_bf16_f32 v105, v106, v107
	v_pk_fma_f32 v[80:81], v[80:81], s[2:3], v[174:175] op_sel_hi:[1,0,0]
	v_cvt_pk_bf16_f32 v100, v100, v101
	v_mul_f32_e32 v82, 0x4b800000, v81
	v_cmp_gt_f32_e64 s[0:1], s3, v81
	v_cmp_gt_f32_e32 vcc, s3, v80
	v_cvt_pk_bf16_f32 v101, v102, v103
	v_cndmask_b32_e64 v81, v81, v82, s[0:1]
	v_rsq_f32_e32 v81, v81
	v_cvt_pk_bf16_f32 v92, v92, v93
	v_cvt_pk_bf16_f32 v93, v94, v95
	v_cvt_pk_bf16_f32 v88, v88, v89
	v_mul_f32_e32 v82, 0x45800000, v81
	v_cndmask_b32_e64 v82, v81, v82, s[0:1]
	v_pk_mul_f32 v[76:77], v[76:77], v[82:83] op_sel_hi:[1,0]
	v_pk_mul_f32 v[78:79], v[78:79], v[82:83] op_sel_hi:[1,0]
	v_pk_mul_f32 v[76:77], v[12:13], v[76:77]
	v_pk_mul_f32 v[78:79], v[14:15], v[78:79]
	v_pk_mul_f32 v[48:49], v[48:49], v[82:83] op_sel_hi:[1,0]
	v_pk_mul_f32 v[50:51], v[50:51], v[82:83] op_sel_hi:[1,0]
	v_cvt_pk_bf16_f32 v76, v76, v77
	v_cvt_pk_bf16_f32 v77, v78, v79
	v_add_co_u32_e64 v78, s[0:1], s25, v146
	v_pk_mul_f32 v[48:49], v[0:1], v[48:49]
	v_pk_mul_f32 v[50:51], v[2:3], v[50:51]
	v_addc_co_u32_e64 v79, s[0:1], -1, v147, s[0:1]
	v_cvt_pk_bf16_f32 v48, v48, v49
	v_cvt_pk_bf16_f32 v49, v50, v51
	global_store_dwordx2 v[78:79], v[48:49], off offset:-2048
	v_mul_f32_e32 v48, 0x4b800000, v80
	v_cndmask_b32_e32 v48, v80, v48, vcc
	v_rsq_f32_e32 v48, v48
	v_pk_mul_f32 v[56:57], v[56:57], v[82:83] op_sel_hi:[1,0]
	v_pk_mul_f32 v[58:59], v[58:59], v[82:83] op_sel_hi:[1,0]
	v_pk_mul_f32 v[52:53], v[52:53], v[82:83] op_sel_hi:[1,0]
	v_mul_f32_e32 v49, 0x45800000, v48
	v_cndmask_b32_e32 v48, v48, v49, vcc
	v_pk_mul_f32 v[32:33], v[32:33], v[48:49] op_sel_hi:[1,0]
	v_pk_mul_f32 v[34:35], v[34:35], v[48:49] op_sel_hi:[1,0]
	v_pk_mul_f32 v[32:33], v[0:1], v[32:33]
	v_pk_mul_f32 v[34:35], v[2:3], v[34:35]
	v_cvt_pk_bf16_f32 v32, v32, v33
	v_cvt_pk_bf16_f32 v33, v34, v35
	global_store_dwordx2 v[146:147], v[32:33], off offset:-4096
	v_mov_b32_e32 v32, v154
	v_mov_b32_e32 v33, v150
	v_mov_b32_e32 v150, v155
	v_pk_add_f32 v[32:33], v[32:33], v[150:151]
	v_mov_b32_e32 v34, v156
	v_mov_b32_e32 v35, v152
	v_pk_add_f32 v[32:33], v[32:33], v[34:35]
	v_mov_b32_e32 v152, v157
	v_pk_add_f32 v[32:33], v[32:33], v[152:153]
	ds_bpermute_b32 v35, v178, v33
	ds_bpermute_b32 v34, v178, v32
	v_pk_mul_f32 v[54:55], v[54:55], v[82:83] op_sel_hi:[1,0]
	v_pk_mul_f32 v[44:45], v[44:45], v[48:49] op_sel_hi:[1,0]
	v_pk_mul_f32 v[46:47], v[46:47], v[48:49] op_sel_hi:[1,0]
	v_pk_mul_f32 v[40:41], v[40:41], v[48:49] op_sel_hi:[1,0]
	s_waitcnt lgkmcnt(0)
; template <bool TO_BF16>
; DI void rms_rows(const int tid, const float* src, const float* gam, bf16_t* dst, float* fdst, int G, int c) {
;     ...
;         for (int o = 32; o > 0; o >>= 1)
; #pragma unroll
;             for (int q = 0; q < NR; ++q) s[q] += __shfl_xor(s[q], o);
; #pragma unroll
;         for (int q = 0; q < NR; ++q) { const float sc = rsqrtf(s[q] * (1.f / 1024.f) + 1e-6f);
; #pragma unroll
;             for (int k = 0; k < 4; ++k) {
;                 if (TO_BF16) { u32x2 o; o.x = pk2(v[q][k][0] * sc * g4[k][0], v[q][k][1] * sc * g4[k][1]); o.y = pk2(v[q][k][2] * sc * g4[k][2], v[q][k][3] * sc * g4[k][3]);
;                     *(u32x2*)(dst + (size_t)(r + q) * 1024 + k * 256 + lane * 4) = o; }
;                 else *(f32x4*)(fdst + (size_t)(r + q) * 1024 + k * 256 + lane * 4) = v[q][k] * sc * g4[k]; } }
	v_pk_add_f32 v[32:33], v[32:33], v[34:35]
	ds_bpermute_b32 v35, v179, v33
	ds_bpermute_b32 v34, v179, v32
	v_pk_mul_f32 v[42:43], v[42:43], v[48:49] op_sel_hi:[1,0]
	v_pk_mul_f32 v[36:37], v[36:37], v[48:49] op_sel_hi:[1,0]
	v_pk_mul_f32 v[38:39], v[38:39], v[48:49] op_sel_hi:[1,0]
	v_pk_mul_f32 v[56:57], v[8:9], v[56:57]
	s_waitcnt lgkmcnt(0)
	v_pk_add_f32 v[32:33], v[32:33], v[34:35]
	ds_bpermute_b32 v35, v180, v33
	ds_bpermute_b32 v34, v180, v32
	v_pk_mul_f32 v[58:59], v[10:11], v[58:59]
	v_pk_mul_f32 v[52:53], v[4:5], v[52:53]
	v_pk_mul_f32 v[54:55], v[6:7], v[54:55]
	v_pk_mul_f32 v[44:45], v[12:13], v[44:45]
	s_waitcnt lgkmcnt(0)
	v_pk_add_f32 v[32:33], v[32:33], v[34:35]
	ds_bpermute_b32 v35, v183, v33
	ds_bpermute_b32 v34, v183, v32
	v_pk_mul_f32 v[46:47], v[14:15], v[46:47]
	v_pk_mul_f32 v[40:41], v[8:9], v[40:41]
	v_pk_mul_f32 v[42:43], v[10:11], v[42:43]
	v_pk_mul_f32 v[36:37], v[4:5], v[36:37]
	s_waitcnt lgkmcnt(0)
	v_pk_add_f32 v[32:33], v[32:33], v[34:35]
	ds_bpermute_b32 v35, v184, v33
	ds_bpermute_b32 v34, v184, v32
	v_pk_mul_f32 v[38:39], v[6:7], v[38:39]
	v_cvt_pk_bf16_f32 v89, v90, v91
	v_cvt_pk_bf16_f32 v84, v84, v85
	v_cvt_pk_bf16_f32 v85, v86, v87
	s_waitcnt lgkmcnt(0)
	v_pk_add_f32 v[32:33], v[32:33], v[34:35]
	ds_bpermute_b32 v35, v185, v33
	ds_bpermute_b32 v34, v185, v32
	v_cvt_pk_bf16_f32 v56, v56, v57
	v_cvt_pk_bf16_f32 v57, v58, v59
	v_cvt_pk_bf16_f32 v52, v52, v53
	v_cvt_pk_bf16_f32 v53, v54, v55
	s_waitcnt lgkmcnt(0)
	v_pk_add_f32 v[32:33], v[32:33], v[34:35]
	v_cvt_pk_bf16_f32 v44, v44, v45
	v_pk_fma_f32 v[32:33], v[32:33], s[2:3], v[174:175] op_sel_hi:[1,0,0]
	v_cvt_pk_bf16_f32 v45, v46, v47
	v_mul_f32_e32 v34, 0x4b800000, v33
	v_cmp_gt_f32_e64 s[0:1], s3, v33
	v_cmp_gt_f32_e32 vcc, s3, v32
	v_cvt_pk_bf16_f32 v40, v40, v41
	v_cndmask_b32_e64 v33, v33, v34, s[0:1]
	v_rsq_f32_e32 v33, v33
	v_cvt_pk_bf16_f32 v41, v42, v43
	v_cvt_pk_bf16_f32 v36, v36, v37
	v_cvt_pk_bf16_f32 v37, v38, v39
	v_mul_f32_e32 v34, 0x45800000, v33
	v_cndmask_b32_e64 v34, v33, v34, s[0:1]
	v_pk_mul_f32 v[16:17], v[16:17], v[34:35] op_sel_hi:[1,0]
	v_pk_mul_f32 v[18:19], v[18:19], v[34:35] op_sel_hi:[1,0]
	v_pk_mul_f32 v[16:17], v[0:1], v[16:17]
	v_pk_mul_f32 v[18:19], v[2:3], v[18:19]
	v_cvt_pk_bf16_f32 v16, v16, v17
	v_cvt_pk_bf16_f32 v17, v18, v19
	global_store_dwordx2 v[146:147], v[16:17], off offset:-2048
	v_mul_f32_e32 v16, 0x4b800000, v32
	v_cndmask_b32_e32 v16, v32, v16, vcc
	v_rsq_f32_e32 v16, v16
	v_pk_mul_f32 v[20:21], v[20:21], v[34:35] op_sel_hi:[1,0]
	v_pk_mul_f32 v[22:23], v[22:23], v[34:35] op_sel_hi:[1,0]
	v_pk_mul_f32 v[20:21], v[4:5], v[20:21]
	v_pk_mul_f32 v[22:23], v[6:7], v[22:23]
	v_mul_f32_e32 v17, 0x45800000, v16
	v_cvt_pk_bf16_f32 v20, v20, v21
	v_cvt_pk_bf16_f32 v21, v22, v23
	v_cndmask_b32_e32 v16, v16, v17, vcc
	global_store_dwordx2 v[146:147], v[20:21], off offset:-2560
	v_pk_mul_f32 v[18:19], v[72:73], v[16:17] op_sel_hi:[1,0]
	v_pk_mul_f32 v[20:21], v[74:75], v[16:17] op_sel_hi:[1,0]
	v_pk_mul_f32 v[18:19], v[12:13], v[18:19]
	v_pk_mul_f32 v[20:21], v[14:15], v[20:21]
	v_cvt_pk_bf16_f32 v18, v18, v19
	v_cvt_pk_bf16_f32 v19, v20, v21
	global_store_dwordx2 v[146:147], v[18:19], off offset:-1536
	v_pk_mul_f32 v[18:19], v[68:69], v[16:17] op_sel_hi:[1,0]
	v_pk_mul_f32 v[20:21], v[70:71], v[16:17] op_sel_hi:[1,0]
	v_pk_mul_f32 v[18:19], v[8:9], v[18:19]
	v_pk_mul_f32 v[20:21], v[10:11], v[20:21]
	v_cvt_pk_bf16_f32 v18, v18, v19
	v_cvt_pk_bf16_f32 v19, v20, v21
	global_store_dwordx2 v[146:147], v[18:19], off offset:-1024
	v_pk_mul_f32 v[18:19], v[64:65], v[16:17] op_sel_hi:[1,0]
	v_pk_mul_f32 v[20:21], v[66:67], v[16:17] op_sel_hi:[1,0]
	v_pk_mul_f32 v[18:19], v[4:5], v[18:19]
	v_pk_mul_f32 v[20:21], v[6:7], v[20:21]
	v_cvt_pk_bf16_f32 v18, v18, v19
	v_cvt_pk_bf16_f32 v19, v20, v21
	v_pk_mul_f32 v[28:29], v[28:29], v[34:35] op_sel_hi:[1,0]
	v_pk_mul_f32 v[30:31], v[30:31], v[34:35] op_sel_hi:[1,0]
	v_pk_mul_f32 v[24:25], v[24:25], v[34:35] op_sel_hi:[1,0]
	v_pk_mul_f32 v[26:27], v[26:27], v[34:35] op_sel_hi:[1,0]
	global_store_dwordx2 v[146:147], v[18:19], off offset:-512
	v_pk_mul_f32 v[18:19], v[60:61], v[16:17] op_sel_hi:[1,0]
	v_pk_mul_f32 v[16:17], v[62:63], v[16:17] op_sel_hi:[1,0]
	v_pk_mul_f32 v[28:29], v[12:13], v[28:29]
	v_pk_mul_f32 v[30:31], v[14:15], v[30:31]
	v_pk_mul_f32 v[24:25], v[8:9], v[24:25]
	v_pk_mul_f32 v[26:27], v[10:11], v[26:27]
	v_pk_mul_f32 v[18:19], v[0:1], v[18:19]
	v_pk_mul_f32 v[16:17], v[2:3], v[16:17]
	v_cvt_pk_bf16_f32 v28, v28, v29
	v_cvt_pk_bf16_f32 v29, v30, v31
	v_cvt_pk_bf16_f32 v24, v24, v25
	v_cvt_pk_bf16_f32 v25, v26, v27
	v_cvt_pk_bf16_f32 v18, v18, v19
	v_cvt_pk_bf16_f32 v19, v16, v17
	v_cmp_lt_i32_e32 vcc, s70, v144
	global_store_dwordx2 v[146:147], v[28:29], off offset:-3584
	global_store_dwordx2 v[146:147], v[24:25], off offset:-3072
	global_store_dwordx2 v[146:147], v[18:19], off
	v_lshl_add_u64 v[146:147], v[146:147], 0, s[16:17]
	s_or_b64 s[14:15], vcc, s[14:15]
	global_store_dwordx2 v[114:115], v[108:109], off offset:-3584
	global_store_dwordx2 v[114:115], v[104:105], off offset:-3072
	global_store_dwordx2 v[114:115], v[100:101], off offset:-2560
	global_store_dwordx2 v[114:115], v[92:93], off offset:-1536
	global_store_dwordx2 v[114:115], v[88:89], off offset:-1024
	global_store_dwordx2 v[114:115], v[84:85], off offset:-512
	global_store_dwordx2 v[78:79], v[76:77], off offset:-3584
	global_store_dwordx2 v[78:79], v[56:57], off offset:-3072
	global_store_dwordx2 v[78:79], v[52:53], off offset:-2560
	global_store_dwordx2 v[78:79], v[44:45], off offset:-1536
	global_store_dwordx2 v[78:79], v[40:41], off offset:-1024
	global_store_dwordx2 v[78:79], v[36:37], off offset:-512
	s_andn2_b64 exec, exec, s[14:15]
	s_cbranch_execnz .LBB0_70

; template <bool TO_BF16>
; DI void rms_rows(const int tid, const float* src, const float* gam, bf16_t* dst, float* fdst, int G, int c) {
;     ...
;     for (int r = (c * 8 + wave) * NR; r < MTOK; r += G * 8 * NR) {
;         f32x4 v[NR][4]; float s[NR];
; #pragma unroll
;         for (int q = 0; q < NR; ++q)
; #pragma unroll
;             for (int k = 0; k < 4; ++k) v[q][k] = *(const f32x4*)(src + (size_t)(r + q) * 1024 + k * 256 + lane * 4);
; #pragma unroll
;         for (int q = 0; q < NR; ++q) { s[q] = 0.f;
; #pragma unroll
;             for (int k = 0; k < 4; ++k) s[q] += v[q][k][0] * v[q][k][0] + v[q][k][1] * v[q][k][1] + v[q][k][2] * v[q][k][2] + v[q][k][3] * v[q][k][3]; }
.LBB0_76:
	v_add_co_u32_e32 v160, vcc, 0xffff9000, v146
	s_nop 1
	v_addc_co_u32_e32 v161, vcc, -1, v147, vcc
	global_load_dwordx4 v[140:143], v[160:161], off offset:-3072
	global_load_dwordx4 v[136:139], v[160:161], off offset:-2048
	global_load_dwordx4 v[132:135], v[160:161], off offset:-1024
	global_load_dwordx4 v[128:131], v[160:161], off
	v_add_co_u32_e32 v158, vcc, 0xffffa000, v146
	s_nop 1
	v_addc_co_u32_e32 v159, vcc, -1, v147, vcc
	global_load_dwordx4 v[104:107], v[158:159], off offset:-3072
	global_load_dwordx4 v[96:99], v[158:159], off offset:-2048
	global_load_dwordx4 v[28:31], v[146:147], off offset:-3072
	global_load_dwordx4 v[24:27], v[146:147], off offset:-2048
	global_load_dwordx4 v[20:23], v[146:147], off offset:-1024
	global_load_dwordx4 v[16:19], v[146:147], off
	global_load_dwordx4 v[124:127], v[158:159], off offset:-1024
	global_load_dwordx4 v[120:123], v[158:159], off
	v_add_co_u32_e32 v156, vcc, 0xffffb000, v146
	s_nop 1
	v_addc_co_u32_e32 v157, vcc, -1, v147, vcc
	global_load_dwordx4 v[116:119], v[156:157], off offset:-3072
	global_load_dwordx4 v[112:115], v[156:157], off offset:-2048
	global_load_dwordx4 v[108:111], v[156:157], off offset:-1024
	global_load_dwordx4 v[100:103], v[156:157], off
	v_add_co_u32_e32 v154, vcc, 0xffffc000, v146
	s_nop 1
	v_addc_co_u32_e32 v155, vcc, -1, v147, vcc
	global_load_dwordx4 v[92:95], v[154:155], off offset:-3072
	global_load_dwordx4 v[88:91], v[154:155], off offset:-2048
	global_load_dwordx4 v[84:87], v[154:155], off offset:-1024
	global_load_dwordx4 v[80:83], v[154:155], off
	v_add_co_u32_e32 v152, vcc, 0xffffd000, v146
	s_nop 1
	v_addc_co_u32_e32 v153, vcc, -1, v147, vcc
	global_load_dwordx4 v[76:79], v[152:153], off offset:-3072
	global_load_dwordx4 v[72:75], v[152:153], off offset:-2048
	global_load_dwordx4 v[68:71], v[152:153], off offset:-1024
	global_load_dwordx4 v[64:67], v[152:153], off
	v_add_co_u32_e32 v150, vcc, 0xffffe000, v146
	s_nop 1
	v_addc_co_u32_e32 v151, vcc, -1, v147, vcc
	global_load_dwordx4 v[60:63], v[150:151], off offset:-3072
	global_load_dwordx4 v[56:59], v[150:151], off offset:-2048
	global_load_dwordx4 v[52:55], v[150:151], off offset:-1024
	global_load_dwordx4 v[44:47], v[150:151], off
	v_add_co_u32_e32 v148, vcc, 0xfffff000, v146
	s_nop 1
	v_addc_co_u32_e32 v149, vcc, -1, v147, vcc
	global_load_dwordx4 v[40:43], v[148:149], off offset:-3072
	global_load_dwordx4 v[36:39], v[148:149], off offset:-2048
	global_load_dwordx4 v[32:35], v[148:149], off offset:-1024
	global_load_dwordx4 v[48:51], v[146:147], off offset:-4096
	v_add_u32_e32 v144, s66, v144
	s_waitcnt vmcnt(31)
	v_mov_b32_e32 v164, v141
	s_waitcnt vmcnt(30)
	v_mov_b32_e32 v165, v137
	v_mov_b32_e32 v162, v140
	v_mov_b32_e32 v163, v136
	s_waitcnt vmcnt(29)
	v_mov_b32_e32 v172, v133
	s_waitcnt vmcnt(28)
	v_mov_b32_e32 v173, v129
	v_pk_mul_f32 v[164:165], v[164:165], v[164:165]
	v_mov_b32_e32 v166, v142
	v_mov_b32_e32 v167, v138
	v_mov_b32_e32 v170, v132
	v_mov_b32_e32 v171, v128
	v_pk_mul_f32 v[172:173], v[172:173], v[172:173]
	v_pk_fma_f32 v[162:163], v[162:163], v[162:163], v[164:165]
	v_mov_b32_e32 v168, v143
	v_mov_b32_e32 v169, v139
	v_mov_b32_e32 v174, v134
	v_mov_b32_e32 v175, v130
	v_pk_fma_f32 v[164:165], v[170:171], v[170:171], v[172:173]
	v_pk_fma_f32 v[162:163], v[166:167], v[166:167], v[162:163]
	s_waitcnt vmcnt(9)
	v_mov_b32_e32 v170, v69
	v_pk_fma_f32 v[166:167], v[168:169], v[168:169], v[162:163]
	v_pk_fma_f32 v[162:163], v[174:175], v[174:175], v[164:165]
	v_mov_b32_e32 v164, v135
	v_mov_b32_e32 v165, v131
	v_mov_b32_e32 v168, v105
	v_mov_b32_e32 v169, v97
	v_pk_fma_f32 v[164:165], v[164:165], v[164:165], v[162:163]
	v_mov_b32_e32 v162, v104
	v_mov_b32_e32 v163, v96
	v_pk_mul_f32 v[168:169], v[168:169], v[168:169]
	s_waitcnt vmcnt(8)
	v_mov_b32_e32 v171, v65
	v_pk_fma_f32 v[162:163], v[162:163], v[162:163], v[168:169]
	v_mov_b32_e32 v168, v106
	v_mov_b32_e32 v169, v98
	v_pk_fma_f32 v[162:163], v[168:169], v[168:169], v[162:163]
	v_mov_b32_e32 v168, v107
	v_mov_b32_e32 v169, v99
	v_pk_fma_f32 v[172:173], v[168:169], v[168:169], v[162:163]
	v_mov_b32_e32 v168, v125
	v_mov_b32_e32 v169, v121
	v_mov_b32_e32 v162, v124
	v_mov_b32_e32 v163, v120
	v_pk_mul_f32 v[168:169], v[168:169], v[168:169]
	v_pk_mul_f32 v[170:171], v[170:171], v[170:171]
	v_pk_fma_f32 v[162:163], v[162:163], v[162:163], v[168:169]
	v_mov_b32_e32 v168, v126
	v_mov_b32_e32 v169, v122
	v_pk_fma_f32 v[162:163], v[168:169], v[168:169], v[162:163]
	v_mov_b32_e32 v168, v127
	v_mov_b32_e32 v169, v123
	v_pk_fma_f32 v[178:179], v[168:169], v[168:169], v[162:163]
	v_mov_b32_e32 v168, v117
	v_mov_b32_e32 v169, v113
	v_mov_b32_e32 v162, v116
	v_mov_b32_e32 v163, v112
	v_pk_mul_f32 v[168:169], v[168:169], v[168:169]
	s_waitcnt vmcnt(7)
	v_mov_b32_e32 v174, v61
	v_pk_fma_f32 v[162:163], v[162:163], v[162:163], v[168:169]
	v_mov_b32_e32 v168, v118
	v_mov_b32_e32 v169, v114
	v_pk_fma_f32 v[162:163], v[168:169], v[168:169], v[162:163]
	v_mov_b32_e32 v168, v119
	v_mov_b32_e32 v169, v115
	v_pk_fma_f32 v[184:185], v[168:169], v[168:169], v[162:163]
	v_mov_b32_e32 v168, v109
	v_mov_b32_e32 v169, v101
	v_mov_b32_e32 v162, v108
	v_mov_b32_e32 v163, v100
	v_pk_mul_f32 v[168:169], v[168:169], v[168:169]
	s_waitcnt vmcnt(6)
; template <bool TO_BF16>
; DI void rms_rows(const int tid, const float* src, const float* gam, bf16_t* dst, float* fdst, int G, int c) {
;     ...
;         for (int q = 0; q < NR; ++q) { s[q] = 0.f;
; #pragma unroll
;             for (int k = 0; k < 4; ++k) s[q] += v[q][k][0] * v[q][k][0] + v[q][k][1] * v[q][k][1] + v[q][k][2] * v[q][k][2] + v[q][k][3] * v[q][k][3]; }
; #pragma unroll
;         for (int o = 32; o > 0; o >>= 1)
; #pragma unroll
;             for (int q = 0; q < NR; ++q) s[q] += __shfl_xor(s[q], o);
	v_mov_b32_e32 v175, v57
	v_pk_fma_f32 v[162:163], v[162:163], v[162:163], v[168:169]
	v_mov_b32_e32 v168, v110
	v_mov_b32_e32 v169, v102
	v_pk_fma_f32 v[162:163], v[168:169], v[168:169], v[162:163]
	v_mov_b32_e32 v168, v111
	v_mov_b32_e32 v169, v103
	v_pk_fma_f32 v[186:187], v[168:169], v[168:169], v[162:163]
	v_mov_b32_e32 v168, v93
	v_mov_b32_e32 v169, v89
	v_mov_b32_e32 v162, v92
	v_mov_b32_e32 v163, v88
	v_pk_mul_f32 v[168:169], v[168:169], v[168:169]
	v_pk_mul_f32 v[174:175], v[174:175], v[174:175]
	v_pk_fma_f32 v[162:163], v[162:163], v[162:163], v[168:169]
	v_mov_b32_e32 v168, v94
	v_mov_b32_e32 v169, v90
	v_pk_fma_f32 v[162:163], v[168:169], v[168:169], v[162:163]
	v_mov_b32_e32 v168, v95
	v_mov_b32_e32 v169, v91
	v_pk_fma_f32 v[188:189], v[168:169], v[168:169], v[162:163]
	v_mov_b32_e32 v168, v85
	v_mov_b32_e32 v169, v81
	v_mov_b32_e32 v162, v84
	v_mov_b32_e32 v163, v80
	v_pk_mul_f32 v[168:169], v[168:169], v[168:169]
	s_waitcnt vmcnt(5)
	v_mov_b32_e32 v176, v53
	v_pk_fma_f32 v[162:163], v[162:163], v[162:163], v[168:169]
	v_mov_b32_e32 v168, v86
	v_mov_b32_e32 v169, v82
	v_pk_fma_f32 v[162:163], v[168:169], v[168:169], v[162:163]
	v_mov_b32_e32 v168, v87
	v_mov_b32_e32 v169, v83
	v_pk_fma_f32 v[190:191], v[168:169], v[168:169], v[162:163]
	v_mov_b32_e32 v168, v77
	v_mov_b32_e32 v169, v73
	v_mov_b32_e32 v162, v76
	v_mov_b32_e32 v163, v72
	v_pk_mul_f32 v[168:169], v[168:169], v[168:169]
	s_waitcnt vmcnt(4)
	v_mov_b32_e32 v177, v45
	v_pk_fma_f32 v[162:163], v[162:163], v[162:163], v[168:169]
	v_mov_b32_e32 v168, v78
	v_mov_b32_e32 v169, v74
	v_pk_fma_f32 v[162:163], v[168:169], v[168:169], v[162:163]
	v_mov_b32_e32 v168, v79
	v_mov_b32_e32 v169, v75
	v_pk_fma_f32 v[168:169], v[168:169], v[168:169], v[162:163]
	v_mov_b32_e32 v162, v68
	v_mov_b32_e32 v163, v64
	v_pk_fma_f32 v[162:163], v[162:163], v[162:163], v[170:171]
	v_mov_b32_e32 v170, v70
	v_mov_b32_e32 v171, v66
	v_pk_fma_f32 v[162:163], v[170:171], v[170:171], v[162:163]
	v_mov_b32_e32 v170, v71
	v_mov_b32_e32 v171, v67
	v_pk_fma_f32 v[170:171], v[170:171], v[170:171], v[162:163]
	v_mov_b32_e32 v162, v60
	v_mov_b32_e32 v163, v56
	v_pk_fma_f32 v[162:163], v[162:163], v[162:163], v[174:175]
	v_mov_b32_e32 v174, v62
	v_mov_b32_e32 v175, v58
	v_pk_fma_f32 v[162:163], v[174:175], v[174:175], v[162:163]
	v_mov_b32_e32 v174, v63
	v_mov_b32_e32 v175, v59
	v_pk_fma_f32 v[174:175], v[174:175], v[174:175], v[162:163]
	v_mov_b32_e32 v162, v52
	v_mov_b32_e32 v163, v44
	v_pk_mul_f32 v[176:177], v[176:177], v[176:177]
	s_waitcnt vmcnt(3)
	v_mov_b32_e32 v196, v41
	v_pk_fma_f32 v[162:163], v[162:163], v[162:163], v[176:177]
	v_mov_b32_e32 v176, v54
	v_mov_b32_e32 v177, v46
	v_pk_fma_f32 v[162:163], v[176:177], v[176:177], v[162:163]
	v_mov_b32_e32 v176, v55
	v_mov_b32_e32 v177, v47
	s_waitcnt vmcnt(2)
	v_mov_b32_e32 v197, v37
	v_pk_fma_f32 v[176:177], v[176:177], v[176:177], v[162:163]
	v_mov_b32_e32 v162, v40
	v_mov_b32_e32 v163, v36
	v_pk_mul_f32 v[196:197], v[196:197], v[196:197]
	s_waitcnt vmcnt(1)
	v_mov_b32_e32 v198, v33
	v_pk_fma_f32 v[162:163], v[162:163], v[162:163], v[196:197]
	v_mov_b32_e32 v196, v42
	v_mov_b32_e32 v197, v38
	v_pk_fma_f32 v[162:163], v[196:197], v[196:197], v[162:163]
	v_mov_b32_e32 v196, v43
	v_mov_b32_e32 v197, v39
	s_waitcnt vmcnt(0)
	v_mov_b32_e32 v199, v49
	v_pk_fma_f32 v[162:163], v[196:197], v[196:197], v[162:163]
	v_mov_b32_e32 v196, v32
	v_mov_b32_e32 v197, v48
	v_pk_mul_f32 v[198:199], v[198:199], v[198:199]
	s_nop 0
	v_pk_fma_f32 v[196:197], v[196:197], v[196:197], v[198:199]
	v_mov_b32_e32 v198, v34
	v_mov_b32_e32 v199, v50
	v_pk_fma_f32 v[196:197], v[198:199], v[198:199], v[196:197]
	v_mov_b32_e32 v198, v172
	v_mov_b32_e32 v199, v166
	v_mov_b32_e32 v166, v173
	v_pk_add_f32 v[166:167], v[198:199], v[166:167]
	v_mov_b32_e32 v172, v178
	v_mov_b32_e32 v173, v164
	v_pk_add_f32 v[166:167], v[166:167], v[172:173]
	v_mov_b32_e32 v164, v179
	v_pk_add_f32 v[164:165], v[166:167], v[164:165]
	ds_bpermute_b32 v173, v180, v165
	ds_bpermute_b32 v172, v180, v164
	v_mov_b32_e32 v166, v35
	v_mov_b32_e32 v167, v51
	v_pk_fma_f32 v[166:167], v[166:167], v[166:167], v[196:197]
	v_mov_b32_e32 v196, v29
	s_waitcnt lgkmcnt(0)
	v_pk_add_f32 v[164:165], v[164:165], v[172:173]
	ds_bpermute_b32 v173, v183, v165
	ds_bpermute_b32 v172, v183, v164
	v_mov_b32_e32 v197, v25
	v_mov_b32_e32 v178, v28
	v_mov_b32_e32 v179, v24
	v_pk_mul_f32 v[196:197], v[196:197], v[196:197]
	s_waitcnt lgkmcnt(0)
	v_pk_add_f32 v[164:165], v[164:165], v[172:173]
	ds_bpermute_b32 v173, v192, v165
	ds_bpermute_b32 v172, v192, v164
	v_pk_fma_f32 v[178:179], v[178:179], v[178:179], v[196:197]
	v_mov_b32_e32 v196, v30
	v_mov_b32_e32 v197, v26
	v_pk_fma_f32 v[178:179], v[196:197], v[196:197], v[178:179]
	s_waitcnt lgkmcnt(0)
	v_pk_add_f32 v[164:165], v[164:165], v[172:173]
	ds_bpermute_b32 v197, v193, v165
	ds_bpermute_b32 v196, v193, v164
	v_mov_b32_e32 v172, v31
	v_mov_b32_e32 v173, v27
	v_mov_b32_e32 v198, v21
	v_mov_b32_e32 v199, v17
	s_waitcnt lgkmcnt(0)
	v_pk_add_f32 v[164:165], v[164:165], v[196:197]
	ds_bpermute_b32 v197, v194, v165
	ds_bpermute_b32 v196, v194, v164
	v_pk_fma_f32 v[172:173], v[172:173], v[172:173], v[178:179]
	v_mov_b32_e32 v178, v20
	v_mov_b32_e32 v179, v16
	v_pk_mul_f32 v[198:199], v[198:199], v[198:199]
	s_waitcnt lgkmcnt(0)
	v_pk_add_f32 v[164:165], v[164:165], v[196:197]
	ds_bpermute_b32 v197, v195, v165
	ds_bpermute_b32 v196, v195, v164
	v_pk_fma_f32 v[178:179], v[178:179], v[178:179], v[198:199]
	v_mov_b32_e32 v198, v22
	v_mov_b32_e32 v199, v18
	v_pk_fma_f32 v[178:179], v[198:199], v[198:199], v[178:179]
	s_waitcnt lgkmcnt(0)
; template <bool TO_BF16>
; DI void rms_rows(const int tid, const float* src, const float* gam, bf16_t* dst, float* fdst, int G, int c) {
;     ...
;         for (int o = 32; o > 0; o >>= 1)
; #pragma unroll
;             for (int q = 0; q < NR; ++q) s[q] += __shfl_xor(s[q], o);
; #pragma unroll
;         for (int q = 0; q < NR; ++q) { const float sc = rsqrtf(s[q] * (1.f / 1024.f) + 1e-6f);
; #pragma unroll
;             for (int k = 0; k < 4; ++k) {
;                 if (TO_BF16) { u32x2 o; o.x = pk2(v[q][k][0] * sc * g4[k][0], v[q][k][1] * sc * g4[k][1]); o.y = pk2(v[q][k][2] * sc * g4[k][2], v[q][k][3] * sc * g4[k][3]);
;                     *(u32x2*)(dst + (size_t)(r + q) * 1024 + k * 256 + lane * 4) = o; }
;                 else *(f32x4*)(fdst + (size_t)(r + q) * 1024 + k * 256 + lane * 4) = v[q][k] * sc * g4[k]; } }
	v_pk_add_f32 v[196:197], v[164:165], v[196:197]
	v_mov_b64_e32 v[164:165], s[14:15]
	v_pk_fma_f32 v[196:197], v[196:197], s[2:3], v[164:165] op_sel_hi:[1,0,0]
	v_mov_b32_e32 v198, v23
	v_mul_f32_e32 v145, 0x4b800000, v197
	v_cmp_gt_f32_e32 vcc, s3, v197
	v_mov_b32_e32 v199, v19
	v_pk_fma_f32 v[178:179], v[198:199], v[198:199], v[178:179]
	v_cndmask_b32_e32 v145, v197, v145, vcc
	v_rsq_f32_e32 v145, v145
	s_nop 0
	v_mul_f32_e32 v197, 0x45800000, v145
	v_cndmask_b32_e32 v198, v145, v197, vcc
	v_pk_mul_f32 v[132:133], v[132:133], v[198:199] op_sel_hi:[1,0]
	v_pk_mul_f32 v[134:135], v[134:135], v[198:199] op_sel_hi:[1,0]
	v_pk_mul_f32 v[132:133], v[8:9], v[132:133]
	v_pk_mul_f32 v[134:135], v[10:11], v[134:135]
	global_store_dwordx4 v[160:161], v[132:135], off offset:-1024
	v_pk_mul_f32 v[136:137], v[136:137], v[198:199] op_sel_hi:[1,0]
	v_pk_mul_f32 v[138:139], v[138:139], v[198:199] op_sel_hi:[1,0]
	v_mov_b32_e32 v132, v188
	v_mov_b32_e32 v133, v184
	v_mov_b32_e32 v184, v189
	v_pk_add_f32 v[132:133], v[132:133], v[184:185]
	v_mov_b32_e32 v134, v190
	v_mov_b32_e32 v135, v186
	v_pk_add_f32 v[132:133], v[132:133], v[134:135]
	v_mov_b32_e32 v186, v191
	v_pk_add_f32 v[132:133], v[132:133], v[186:187]
	ds_bpermute_b32 v135, v180, v133
	ds_bpermute_b32 v134, v180, v132
	v_pk_mul_f32 v[138:139], v[6:7], v[138:139]
	v_pk_mul_f32 v[136:137], v[4:5], v[136:137]
	global_store_dwordx4 v[160:161], v[136:139], off offset:-2048
	v_cmp_gt_f32_e32 vcc, s3, v196
	s_waitcnt lgkmcnt(0)
	v_pk_add_f32 v[132:133], v[132:133], v[134:135]
	ds_bpermute_b32 v135, v183, v133
	ds_bpermute_b32 v134, v183, v132
	v_mul_f32_e32 v136, 0x4b800000, v196
	v_cndmask_b32_e32 v136, v196, v136, vcc
	v_pk_mul_f32 v[128:129], v[128:129], v[198:199] op_sel_hi:[1,0]
	v_pk_mul_f32 v[130:131], v[130:131], v[198:199] op_sel_hi:[1,0]
	v_rsq_f32_e32 v136, v136
	v_pk_mul_f32 v[130:131], v[14:15], v[130:131]
	v_pk_mul_f32 v[128:129], v[12:13], v[128:129]
	global_store_dwordx4 v[160:161], v[128:131], off
	v_pk_mul_f32 v[140:141], v[140:141], v[198:199] op_sel_hi:[1,0]
	v_pk_mul_f32 v[142:143], v[142:143], v[198:199] op_sel_hi:[1,0]
	s_waitcnt lgkmcnt(0)
	v_pk_add_f32 v[130:131], v[132:133], v[134:135]
	ds_bpermute_b32 v133, v192, v131
	ds_bpermute_b32 v132, v192, v130
	v_mul_f32_e32 v128, 0x45800000, v136
	v_cndmask_b32_e32 v128, v136, v128, vcc
	v_pk_mul_f32 v[104:105], v[104:105], v[128:129] op_sel_hi:[1,0]
	v_pk_mul_f32 v[106:107], v[106:107], v[128:129] op_sel_hi:[1,0]
	v_pk_mul_f32 v[104:105], v[0:1], v[104:105]
	v_pk_mul_f32 v[106:107], v[2:3], v[106:107]
	global_store_dwordx4 v[158:159], v[104:107], off offset:-3072
	v_pk_mul_f32 v[96:97], v[96:97], v[128:129] op_sel_hi:[1,0]
	v_pk_mul_f32 v[98:99], v[98:99], v[128:129] op_sel_hi:[1,0]
	s_waitcnt lgkmcnt(0)
	v_pk_add_f32 v[104:105], v[130:131], v[132:133]
	ds_bpermute_b32 v107, v193, v105
	ds_bpermute_b32 v106, v193, v104
	v_pk_mul_f32 v[98:99], v[6:7], v[98:99]
	v_pk_mul_f32 v[96:97], v[4:5], v[96:97]
	global_store_dwordx4 v[158:159], v[96:99], off offset:-2048
	v_pk_mul_f32 v[142:143], v[2:3], v[142:143]
	s_waitcnt lgkmcnt(0)
	v_pk_add_f32 v[104:105], v[104:105], v[106:107]
	ds_bpermute_b32 v107, v194, v105
	ds_bpermute_b32 v106, v194, v104
	v_pk_mul_f32 v[96:97], v[124:125], v[128:129] op_sel_hi:[1,0]
	v_pk_mul_f32 v[98:99], v[126:127], v[128:129] op_sel_hi:[1,0]
	v_pk_mul_f32 v[96:97], v[8:9], v[96:97]
	v_pk_mul_f32 v[98:99], v[10:11], v[98:99]
	s_waitcnt lgkmcnt(0)
	v_pk_add_f32 v[104:105], v[104:105], v[106:107]
	ds_bpermute_b32 v107, v195, v105
	ds_bpermute_b32 v106, v195, v104
	global_store_dwordx4 v[158:159], v[96:99], off offset:-1024
	v_pk_mul_f32 v[140:141], v[0:1], v[140:141]
	global_store_dwordx4 v[160:161], v[140:143], off offset:-3072
	v_pk_mul_f32 v[96:97], v[120:121], v[128:129] op_sel_hi:[1,0]
	s_waitcnt lgkmcnt(0)
	v_pk_add_f32 v[104:105], v[104:105], v[106:107]
	v_pk_mul_f32 v[98:99], v[122:123], v[128:129] op_sel_hi:[1,0]
	v_pk_fma_f32 v[104:105], v[104:105], s[2:3], v[164:165] op_sel_hi:[1,0,0]
	v_pk_mul_f32 v[98:99], v[14:15], v[98:99]
	v_mul_f32_e32 v106, 0x4b800000, v105
	v_cmp_gt_f32_e32 vcc, s3, v105
	v_pk_mul_f32 v[96:97], v[12:13], v[96:97]
	global_store_dwordx4 v[158:159], v[96:99], off
	v_cndmask_b32_e32 v105, v105, v106, vcc
	v_rsq_f32_e32 v105, v105
	s_nop 0
	v_mul_f32_e32 v96, 0x45800000, v105
	v_cndmask_b32_e32 v106, v105, v96, vcc
	v_pk_mul_f32 v[96:97], v[116:117], v[106:107] op_sel_hi:[1,0]
	v_pk_mul_f32 v[98:99], v[118:119], v[106:107] op_sel_hi:[1,0]
	v_pk_mul_f32 v[96:97], v[0:1], v[96:97]
	v_pk_mul_f32 v[98:99], v[2:3], v[98:99]
	global_store_dwordx4 v[156:157], v[96:99], off offset:-3072
	v_mul_f32_e32 v105, 0x4b800000, v104
	v_cmp_gt_f32_e32 vcc, s3, v104
	v_pk_mul_f32 v[96:97], v[112:113], v[106:107] op_sel_hi:[1,0]
	v_pk_mul_f32 v[98:99], v[114:115], v[106:107] op_sel_hi:[1,0]
	v_pk_mul_f32 v[96:97], v[4:5], v[96:97]
	v_pk_mul_f32 v[98:99], v[6:7], v[98:99]
	global_store_dwordx4 v[156:157], v[96:99], off offset:-2048
	v_cndmask_b32_e32 v104, v104, v105, vcc
	v_rsq_f32_e32 v104, v104
	v_pk_mul_f32 v[96:97], v[108:109], v[106:107] op_sel_hi:[1,0]
	v_pk_mul_f32 v[98:99], v[110:111], v[106:107] op_sel_hi:[1,0]
	v_pk_mul_f32 v[96:97], v[8:9], v[96:97]
	v_pk_mul_f32 v[98:99], v[10:11], v[98:99]
	global_store_dwordx4 v[156:157], v[96:99], off offset:-1024
	s_nop 1
	v_pk_mul_f32 v[96:97], v[100:101], v[106:107] op_sel_hi:[1,0]
	v_mov_b32_e32 v100, v174
	v_mov_b32_e32 v101, v168
	v_mov_b32_e32 v168, v175
	v_pk_mul_f32 v[98:99], v[102:103], v[106:107] op_sel_hi:[1,0]
	v_pk_add_f32 v[100:101], v[100:101], v[168:169]
	v_mov_b32_e32 v102, v176
	v_mov_b32_e32 v103, v170
	v_pk_add_f32 v[100:101], v[100:101], v[102:103]
	v_mov_b32_e32 v170, v177
	v_pk_add_f32 v[100:101], v[100:101], v[170:171]
	ds_bpermute_b32 v103, v180, v101
	ds_bpermute_b32 v102, v180, v100
	v_pk_mul_f32 v[98:99], v[14:15], v[98:99]
	v_pk_mul_f32 v[96:97], v[12:13], v[96:97]
	global_store_dwordx4 v[156:157], v[96:99], off
	s_waitcnt lgkmcnt(0)
; template <bool TO_BF16>
; DI void rms_rows(const int tid, const float* src, const float* gam, bf16_t* dst, float* fdst, int G, int c) {
;     ...
;         for (int o = 32; o > 0; o >>= 1)
; #pragma unroll
;             for (int q = 0; q < NR; ++q) s[q] += __shfl_xor(s[q], o);
; #pragma unroll
;         for (int q = 0; q < NR; ++q) { const float sc = rsqrtf(s[q] * (1.f / 1024.f) + 1e-6f);
; #pragma unroll
;             for (int k = 0; k < 4; ++k) {
;                 if (TO_BF16) { u32x2 o; o.x = pk2(v[q][k][0] * sc * g4[k][0], v[q][k][1] * sc * g4[k][1]); o.y = pk2(v[q][k][2] * sc * g4[k][2], v[q][k][3] * sc * g4[k][3]);
;                     *(u32x2*)(dst + (size_t)(r + q) * 1024 + k * 256 + lane * 4) = o; }
;                 else *(f32x4*)(fdst + (size_t)(r + q) * 1024 + k * 256 + lane * 4) = v[q][k] * sc * g4[k]; } }
	v_pk_add_f32 v[100:101], v[100:101], v[102:103]
	ds_bpermute_b32 v103, v183, v101
	ds_bpermute_b32 v102, v183, v100
	v_mul_f32_e32 v96, 0x45800000, v104
	v_cndmask_b32_e32 v96, v104, v96, vcc
	v_pk_mul_f32 v[92:93], v[92:93], v[96:97] op_sel_hi:[1,0]
	v_pk_mul_f32 v[94:95], v[94:95], v[96:97] op_sel_hi:[1,0]
	s_waitcnt lgkmcnt(0)
	v_pk_add_f32 v[98:99], v[100:101], v[102:103]
	ds_bpermute_b32 v101, v192, v99
	ds_bpermute_b32 v100, v192, v98
	v_pk_mul_f32 v[94:95], v[2:3], v[94:95]
	v_pk_mul_f32 v[92:93], v[0:1], v[92:93]
	global_store_dwordx4 v[154:155], v[92:95], off offset:-3072
	v_pk_mul_f32 v[88:89], v[88:89], v[96:97] op_sel_hi:[1,0]
	v_pk_mul_f32 v[90:91], v[90:91], v[96:97] op_sel_hi:[1,0]
	s_waitcnt lgkmcnt(0)
	v_pk_add_f32 v[92:93], v[98:99], v[100:101]
	ds_bpermute_b32 v95, v193, v93
	ds_bpermute_b32 v94, v193, v92
	v_pk_mul_f32 v[90:91], v[6:7], v[90:91]
	v_pk_mul_f32 v[88:89], v[4:5], v[88:89]
	global_store_dwordx4 v[154:155], v[88:91], off offset:-2048
	v_pk_mul_f32 v[84:85], v[84:85], v[96:97] op_sel_hi:[1,0]
	s_waitcnt lgkmcnt(0)
	v_pk_add_f32 v[92:93], v[92:93], v[94:95]
	ds_bpermute_b32 v95, v194, v93
	ds_bpermute_b32 v94, v194, v92
	v_pk_mul_f32 v[86:87], v[86:87], v[96:97] op_sel_hi:[1,0]
	v_pk_mul_f32 v[84:85], v[8:9], v[84:85]
	v_pk_mul_f32 v[86:87], v[10:11], v[86:87]
	global_store_dwordx4 v[154:155], v[84:87], off offset:-1024
	s_waitcnt lgkmcnt(0)
	v_pk_add_f32 v[88:89], v[92:93], v[94:95]
	ds_bpermute_b32 v91, v195, v89
	ds_bpermute_b32 v90, v195, v88
	v_pk_mul_f32 v[80:81], v[80:81], v[96:97] op_sel_hi:[1,0]
	v_pk_mul_f32 v[82:83], v[82:83], v[96:97] op_sel_hi:[1,0]
	v_pk_mul_f32 v[80:81], v[12:13], v[80:81]
	v_pk_mul_f32 v[82:83], v[14:15], v[82:83]
	s_waitcnt lgkmcnt(0)
	v_pk_add_f32 v[84:85], v[88:89], v[90:91]
	global_store_dwordx4 v[154:155], v[80:83], off
	v_pk_fma_f32 v[84:85], v[84:85], s[2:3], v[164:165] op_sel_hi:[1,0,0]
	s_nop 0
	v_mul_f32_e32 v86, 0x4b800000, v85
	v_cmp_gt_f32_e32 vcc, s3, v85
	s_nop 1
	v_cndmask_b32_e32 v85, v85, v86, vcc
	v_rsq_f32_e32 v85, v85
	s_nop 0
	v_mul_f32_e32 v80, 0x45800000, v85
	v_cndmask_b32_e32 v80, v85, v80, vcc
	v_pk_mul_f32 v[68:69], v[68:69], v[80:81] op_sel_hi:[1,0]
	v_pk_mul_f32 v[70:71], v[70:71], v[80:81] op_sel_hi:[1,0]
	v_pk_mul_f32 v[68:69], v[8:9], v[68:69]
	v_pk_mul_f32 v[70:71], v[10:11], v[70:71]
	global_store_dwordx4 v[152:153], v[68:71], off offset:-1024
	v_pk_mul_f32 v[72:73], v[72:73], v[80:81] op_sel_hi:[1,0]
	v_pk_mul_f32 v[74:75], v[74:75], v[80:81] op_sel_hi:[1,0]
	v_mov_b32_e32 v68, v172
	v_mov_b32_e32 v69, v162
	v_mov_b32_e32 v162, v173
	v_pk_add_f32 v[68:69], v[68:69], v[162:163]
	v_mov_b32_e32 v70, v178
	v_mov_b32_e32 v71, v166
	v_pk_add_f32 v[68:69], v[68:69], v[70:71]
	v_mov_b32_e32 v166, v179
	v_pk_add_f32 v[68:69], v[68:69], v[166:167]
	ds_bpermute_b32 v71, v180, v69
	ds_bpermute_b32 v70, v180, v68
	v_pk_mul_f32 v[74:75], v[6:7], v[74:75]
	v_pk_mul_f32 v[72:73], v[4:5], v[72:73]
	global_store_dwordx4 v[152:153], v[72:75], off offset:-2048
	v_cmp_gt_f32_e32 vcc, s3, v84
	s_waitcnt lgkmcnt(0)
	v_pk_add_f32 v[68:69], v[68:69], v[70:71]
	ds_bpermute_b32 v71, v183, v69
	ds_bpermute_b32 v70, v183, v68
	v_mul_f32_e32 v72, 0x4b800000, v84
	v_cndmask_b32_e32 v72, v84, v72, vcc
	v_pk_mul_f32 v[64:65], v[64:65], v[80:81] op_sel_hi:[1,0]
	v_pk_mul_f32 v[66:67], v[66:67], v[80:81] op_sel_hi:[1,0]
	v_rsq_f32_e32 v72, v72
	v_pk_mul_f32 v[66:67], v[14:15], v[66:67]
	v_pk_mul_f32 v[64:65], v[12:13], v[64:65]
	global_store_dwordx4 v[152:153], v[64:67], off
	v_pk_mul_f32 v[76:77], v[76:77], v[80:81] op_sel_hi:[1,0]
	v_pk_mul_f32 v[78:79], v[78:79], v[80:81] op_sel_hi:[1,0]
	s_waitcnt lgkmcnt(0)
	v_pk_add_f32 v[66:67], v[68:69], v[70:71]
	ds_bpermute_b32 v69, v192, v67
	ds_bpermute_b32 v68, v192, v66
	v_mul_f32_e32 v64, 0x45800000, v72
	v_cndmask_b32_e32 v64, v72, v64, vcc
	v_pk_mul_f32 v[60:61], v[60:61], v[64:65] op_sel_hi:[1,0]
	v_pk_mul_f32 v[62:63], v[62:63], v[64:65] op_sel_hi:[1,0]
	v_pk_mul_f32 v[60:61], v[0:1], v[60:61]
	v_pk_mul_f32 v[62:63], v[2:3], v[62:63]
	global_store_dwordx4 v[150:151], v[60:63], off offset:-3072
	v_pk_mul_f32 v[56:57], v[56:57], v[64:65] op_sel_hi:[1,0]
	v_pk_mul_f32 v[58:59], v[58:59], v[64:65] op_sel_hi:[1,0]
	s_waitcnt lgkmcnt(0)
; template <bool TO_BF16>
; DI void rms_rows(const int tid, const float* src, const float* gam, bf16_t* dst, float* fdst, int G, int c) {
;     ...
;         for (int o = 32; o > 0; o >>= 1)
; #pragma unroll
;             for (int q = 0; q < NR; ++q) s[q] += __shfl_xor(s[q], o);
; #pragma unroll
;         for (int q = 0; q < NR; ++q) { const float sc = rsqrtf(s[q] * (1.f / 1024.f) + 1e-6f);
; #pragma unroll
;             for (int k = 0; k < 4; ++k) {
;                 if (TO_BF16) { u32x2 o; o.x = pk2(v[q][k][0] * sc * g4[k][0], v[q][k][1] * sc * g4[k][1]); o.y = pk2(v[q][k][2] * sc * g4[k][2], v[q][k][3] * sc * g4[k][3]);
;                     *(u32x2*)(dst + (size_t)(r + q) * 1024 + k * 256 + lane * 4) = o; }
;                 else *(f32x4*)(fdst + (size_t)(r + q) * 1024 + k * 256 + lane * 4) = v[q][k] * sc * g4[k]; } }
	v_pk_add_f32 v[60:61], v[66:67], v[68:69]
	ds_bpermute_b32 v63, v193, v61
	ds_bpermute_b32 v62, v193, v60
	v_pk_mul_f32 v[58:59], v[6:7], v[58:59]
	v_pk_mul_f32 v[56:57], v[4:5], v[56:57]
	global_store_dwordx4 v[150:151], v[56:59], off offset:-2048
	v_pk_mul_f32 v[52:53], v[52:53], v[64:65] op_sel_hi:[1,0]
	s_waitcnt lgkmcnt(0)
	v_pk_add_f32 v[60:61], v[60:61], v[62:63]
	ds_bpermute_b32 v63, v194, v61
	ds_bpermute_b32 v62, v194, v60
	v_pk_mul_f32 v[54:55], v[54:55], v[64:65] op_sel_hi:[1,0]
	v_pk_mul_f32 v[52:53], v[8:9], v[52:53]
	v_pk_mul_f32 v[54:55], v[10:11], v[54:55]
	global_store_dwordx4 v[150:151], v[52:55], off offset:-1024
	s_waitcnt lgkmcnt(0)
	v_pk_add_f32 v[56:57], v[60:61], v[62:63]
	ds_bpermute_b32 v59, v195, v57
	ds_bpermute_b32 v58, v195, v56
	v_pk_mul_f32 v[44:45], v[44:45], v[64:65] op_sel_hi:[1,0]
	v_pk_mul_f32 v[46:47], v[46:47], v[64:65] op_sel_hi:[1,0]
	v_pk_mul_f32 v[44:45], v[12:13], v[44:45]
	v_pk_mul_f32 v[46:47], v[14:15], v[46:47]
	s_waitcnt lgkmcnt(0)
	v_pk_add_f32 v[52:53], v[56:57], v[58:59]
	global_store_dwordx4 v[150:151], v[44:47], off
	v_pk_fma_f32 v[52:53], v[52:53], s[2:3], v[164:165] op_sel_hi:[1,0,0]
	v_pk_mul_f32 v[78:79], v[2:3], v[78:79]
	v_mul_f32_e32 v54, 0x4b800000, v53
	v_cmp_gt_f32_e32 vcc, s3, v53
	v_pk_mul_f32 v[76:77], v[0:1], v[76:77]
	global_store_dwordx4 v[152:153], v[76:79], off offset:-3072
	v_cndmask_b32_e32 v53, v53, v54, vcc
	v_rsq_f32_e32 v53, v53
	s_nop 0
	v_mul_f32_e32 v44, 0x45800000, v53
	v_cndmask_b32_e32 v44, v53, v44, vcc
	v_pk_mul_f32 v[36:37], v[36:37], v[44:45] op_sel_hi:[1,0]
	v_pk_mul_f32 v[38:39], v[38:39], v[44:45] op_sel_hi:[1,0]
	v_pk_mul_f32 v[36:37], v[4:5], v[36:37]
	v_pk_mul_f32 v[38:39], v[6:7], v[38:39]
	global_store_dwordx4 v[148:149], v[36:39], off offset:-2048
	v_cmp_gt_f32_e32 vcc, s3, v52
	v_pk_mul_f32 v[32:33], v[32:33], v[44:45] op_sel_hi:[1,0]
	v_mul_f32_e32 v36, 0x4b800000, v52
	v_cndmask_b32_e32 v36, v52, v36, vcc
	v_pk_mul_f32 v[34:35], v[34:35], v[44:45] op_sel_hi:[1,0]
	v_rsq_f32_e32 v36, v36
	v_pk_mul_f32 v[34:35], v[10:11], v[34:35]
	v_pk_mul_f32 v[32:33], v[8:9], v[32:33]
	global_store_dwordx4 v[148:149], v[32:35], off offset:-1024
	v_pk_mul_f32 v[40:41], v[40:41], v[44:45] op_sel_hi:[1,0]
	v_pk_mul_f32 v[42:43], v[42:43], v[44:45] op_sel_hi:[1,0]
	v_pk_mul_f32 v[32:33], v[48:49], v[44:45] op_sel_hi:[1,0]
	v_pk_mul_f32 v[34:35], v[50:51], v[44:45] op_sel_hi:[1,0]
	v_pk_mul_f32 v[32:33], v[12:13], v[32:33]
	v_pk_mul_f32 v[34:35], v[14:15], v[34:35]
	global_store_dwordx4 v[146:147], v[32:35], off offset:-4096
	v_pk_mul_f32 v[42:43], v[2:3], v[42:43]
	v_pk_mul_f32 v[40:41], v[0:1], v[40:41]
	v_mul_f32_e32 v32, 0x45800000, v36
	v_cndmask_b32_e32 v32, v36, v32, vcc
	v_pk_mul_f32 v[28:29], v[28:29], v[32:33] op_sel_hi:[1,0]
	v_pk_mul_f32 v[30:31], v[30:31], v[32:33] op_sel_hi:[1,0]
	v_pk_mul_f32 v[24:25], v[24:25], v[32:33] op_sel_hi:[1,0]
	v_pk_mul_f32 v[26:27], v[26:27], v[32:33] op_sel_hi:[1,0]
	v_pk_mul_f32 v[20:21], v[20:21], v[32:33] op_sel_hi:[1,0]
	v_pk_mul_f32 v[22:23], v[22:23], v[32:33] op_sel_hi:[1,0]
	v_pk_mul_f32 v[16:17], v[16:17], v[32:33] op_sel_hi:[1,0]
	v_pk_mul_f32 v[18:19], v[18:19], v[32:33] op_sel_hi:[1,0]
	v_pk_mul_f32 v[30:31], v[2:3], v[30:31]
	v_pk_mul_f32 v[28:29], v[0:1], v[28:29]
	v_pk_mul_f32 v[26:27], v[6:7], v[26:27]
	v_pk_mul_f32 v[24:25], v[4:5], v[24:25]
	v_pk_mul_f32 v[22:23], v[10:11], v[22:23]
	v_pk_mul_f32 v[20:21], v[8:9], v[20:21]
	v_pk_mul_f32 v[18:19], v[14:15], v[18:19]
	v_pk_mul_f32 v[16:17], v[12:13], v[16:17]
	v_cmp_lt_i32_e32 vcc, s70, v144
	global_store_dwordx4 v[146:147], v[28:31], off offset:-3072
	global_store_dwordx4 v[146:147], v[24:27], off offset:-2048
	global_store_dwordx4 v[146:147], v[20:23], off offset:-1024
	global_store_dwordx4 v[146:147], v[16:19], off
	s_or_b64 s[4:5], vcc, s[4:5]
	v_lshl_add_u64 v[146:147], v[146:147], 0, s[62:63]
	global_store_dwordx4 v[148:149], v[40:43], off offset:-3072
	s_andn2_b64 exec, exec, s[4:5]
	s_cbranch_execnz .LBB0_76

; template <bool TO_BF16>
; DI void rms_rows(const int tid, const float* src, const float* gam, bf16_t* dst, float* fdst, int G, int c) {
;     ...
;     for (int r = (c * 8 + wave) * NR; r < MTOK; r += G * 8 * NR) {
;         f32x4 v[NR][4]; float s[NR];
; #pragma unroll
;         for (int q = 0; q < NR; ++q)
; #pragma unroll
;             for (int k = 0; k < 4; ++k) v[q][k] = *(const f32x4*)(src + (size_t)(r + q) * 1024 + k * 256 + lane * 4);
; #pragma unroll
;         for (int q = 0; q < NR; ++q) { s[q] = 0.f;
; #pragma unroll
;             for (int k = 0; k < 4; ++k) s[q] += v[q][k][0] * v[q][k][0] + v[q][k][1] * v[q][k][1] + v[q][k][2] * v[q][k][2] + v[q][k][3] * v[q][k][3]; }
.LBB0_394:
	v_add_co_u32_e32 v16, vcc, 0xffff9000, v148
	s_nop 1
	v_addc_co_u32_e32 v17, vcc, -1, v149, vcc
	global_load_dwordx4 v[140:143], v[16:17], off offset:-3072
	global_load_dwordx4 v[136:139], v[16:17], off offset:-2048
	global_load_dwordx4 v[132:135], v[16:17], off offset:-1024
	global_load_dwordx4 v[128:131], v[16:17], off
	v_add_co_u32_e32 v16, vcc, 0xffffa000, v148
	s_nop 1
	v_addc_co_u32_e32 v17, vcc, -1, v149, vcc
	global_load_dwordx4 v[124:127], v[16:17], off offset:-3072
	global_load_dwordx4 v[120:123], v[16:17], off offset:-2048
	global_load_dwordx4 v[116:119], v[16:17], off offset:-1024
	global_load_dwordx4 v[112:115], v[16:17], off
	v_add_co_u32_e32 v16, vcc, 0xffffb000, v148
	s_nop 1
	v_addc_co_u32_e32 v17, vcc, -1, v149, vcc
	global_load_dwordx4 v[108:111], v[16:17], off offset:-3072
	global_load_dwordx4 v[104:107], v[16:17], off offset:-2048
	global_load_dwordx4 v[100:103], v[16:17], off offset:-1024
	global_load_dwordx4 v[96:99], v[16:17], off
	v_add_co_u32_e32 v16, vcc, 0xffffc000, v148
	s_nop 1
	v_addc_co_u32_e32 v17, vcc, -1, v149, vcc
	global_load_dwordx4 v[92:95], v[16:17], off offset:-3072
	global_load_dwordx4 v[88:91], v[16:17], off offset:-2048
	global_load_dwordx4 v[84:87], v[16:17], off offset:-1024
	global_load_dwordx4 v[80:83], v[16:17], off
	v_add_co_u32_e32 v16, vcc, 0xffffd000, v148
	s_nop 1
	v_addc_co_u32_e32 v17, vcc, -1, v149, vcc
	global_load_dwordx4 v[76:79], v[16:17], off offset:-3072
	global_load_dwordx4 v[56:59], v[16:17], off offset:-2048
	global_load_dwordx4 v[52:55], v[16:17], off offset:-1024
	global_load_dwordx4 v[48:51], v[16:17], off
	v_add_co_u32_e32 v16, vcc, 0xffffe000, v148
	s_nop 1
	v_addc_co_u32_e32 v17, vcc, -1, v149, vcc
	global_load_dwordx4 v[44:47], v[16:17], off offset:-3072
	global_load_dwordx4 v[40:43], v[16:17], off offset:-2048
	global_load_dwordx4 v[36:39], v[16:17], off offset:-1024
	global_load_dwordx4 v[32:35], v[16:17], off
	v_add_co_u32_e32 v16, vcc, 0xfffff000, v148
	s_nop 1
	v_addc_co_u32_e32 v17, vcc, -1, v149, vcc
	global_load_dwordx4 v[28:31], v[16:17], off offset:-3072
	global_load_dwordx4 v[24:27], v[16:17], off offset:-2048
	global_load_dwordx4 v[20:23], v[16:17], off offset:-1024
	global_load_dwordx4 v[16:19], v[148:149], off offset:-4096
	global_load_dwordx4 v[72:75], v[148:149], off offset:-3072
	global_load_dwordx4 v[68:71], v[148:149], off offset:-2048
	global_load_dwordx4 v[64:67], v[148:149], off offset:-1024
	global_load_dwordx4 v[60:63], v[148:149], off
	v_add_u32_e32 v144, s66, v144
	s_waitcnt vmcnt(31)
	v_mov_b32_e32 v152, v141
	s_waitcnt vmcnt(30)
	v_mov_b32_e32 v153, v137
	v_mov_b32_e32 v150, v140
	v_mov_b32_e32 v151, v136
	v_pk_mul_f32 v[152:153], v[152:153], v[152:153]
	s_nop 0
	v_pk_fma_f32 v[150:151], v[150:151], v[150:151], v[152:153]
	v_mov_b32_e32 v152, v142
	v_mov_b32_e32 v153, v138
	v_pk_fma_f32 v[150:151], v[152:153], v[152:153], v[150:151]
	v_mov_b32_e32 v152, v143
	v_mov_b32_e32 v153, v139
	v_pk_fma_f32 v[174:175], v[152:153], v[152:153], v[150:151]
	s_waitcnt vmcnt(29)
	v_mov_b32_e32 v152, v133
	s_waitcnt vmcnt(28)
	v_mov_b32_e32 v153, v129
	v_mov_b32_e32 v150, v132
	v_mov_b32_e32 v151, v128
	v_pk_mul_f32 v[152:153], v[152:153], v[152:153]
	v_lshl_add_u64 v[148:149], v[148:149], 0, s[62:63]
	v_pk_fma_f32 v[150:151], v[150:151], v[150:151], v[152:153]
	v_mov_b32_e32 v152, v134
	v_mov_b32_e32 v153, v130
	v_pk_fma_f32 v[150:151], v[152:153], v[152:153], v[150:151]
	v_mov_b32_e32 v152, v135
	v_mov_b32_e32 v153, v131
	v_pk_fma_f32 v[176:177], v[152:153], v[152:153], v[150:151]
	s_waitcnt vmcnt(27)
	v_mov_b32_e32 v152, v125
	s_waitcnt vmcnt(26)
	v_mov_b32_e32 v153, v121
	v_mov_b32_e32 v150, v124
	v_mov_b32_e32 v151, v120
	v_pk_mul_f32 v[152:153], v[152:153], v[152:153]
	s_waitcnt vmcnt(5)
	v_mov_b32_e32 v154, v21
	v_pk_fma_f32 v[150:151], v[150:151], v[150:151], v[152:153]
	v_mov_b32_e32 v152, v126
	v_mov_b32_e32 v153, v122
	v_pk_fma_f32 v[150:151], v[152:153], v[152:153], v[150:151]
	v_mov_b32_e32 v152, v127
	v_mov_b32_e32 v153, v123
	v_pk_fma_f32 v[186:187], v[152:153], v[152:153], v[150:151]
	v_mov_b32_e32 v152, v117
	v_mov_b32_e32 v153, v113
	v_mov_b32_e32 v150, v116
	v_mov_b32_e32 v151, v112
	v_pk_mul_f32 v[152:153], v[152:153], v[152:153]
	s_waitcnt vmcnt(4)
	v_mov_b32_e32 v155, v17
	v_pk_fma_f32 v[150:151], v[150:151], v[150:151], v[152:153]
	v_mov_b32_e32 v152, v118
	v_mov_b32_e32 v153, v114
	v_pk_fma_f32 v[150:151], v[152:153], v[152:153], v[150:151]
	v_mov_b32_e32 v152, v119
	v_mov_b32_e32 v153, v115
	v_pk_fma_f32 v[188:189], v[152:153], v[152:153], v[150:151]
	v_mov_b32_e32 v152, v109
	v_mov_b32_e32 v153, v105
	v_mov_b32_e32 v150, v108
	v_mov_b32_e32 v151, v104
	v_pk_mul_f32 v[152:153], v[152:153], v[152:153]
	v_pk_mul_f32 v[154:155], v[154:155], v[154:155]
	v_pk_fma_f32 v[150:151], v[150:151], v[150:151], v[152:153]
	v_mov_b32_e32 v152, v110
	v_mov_b32_e32 v153, v106
	v_pk_fma_f32 v[150:151], v[152:153], v[152:153], v[150:151]
	v_mov_b32_e32 v152, v111
	v_mov_b32_e32 v153, v107
	v_pk_fma_f32 v[166:167], v[152:153], v[152:153], v[150:151]
	v_mov_b32_e32 v152, v101
	v_mov_b32_e32 v153, v97
	v_mov_b32_e32 v150, v100
	v_mov_b32_e32 v151, v96
	v_pk_mul_f32 v[152:153], v[152:153], v[152:153]
	s_waitcnt vmcnt(3)
	v_mov_b32_e32 v156, v73
	v_pk_fma_f32 v[150:151], v[150:151], v[150:151], v[152:153]
	v_mov_b32_e32 v152, v102
	v_mov_b32_e32 v153, v98
	v_pk_fma_f32 v[150:151], v[152:153], v[152:153], v[150:151]
	v_mov_b32_e32 v152, v103
	v_mov_b32_e32 v153, v99
	v_pk_fma_f32 v[168:169], v[152:153], v[152:153], v[150:151]
	v_mov_b32_e32 v152, v93
	v_mov_b32_e32 v153, v89
	v_mov_b32_e32 v150, v92
	v_mov_b32_e32 v151, v88
	v_pk_mul_f32 v[152:153], v[152:153], v[152:153]
	s_waitcnt vmcnt(2)
; template <bool TO_BF16>
; DI void rms_rows(const int tid, const float* src, const float* gam, bf16_t* dst, float* fdst, int G, int c) {
;     ...
;         for (int q = 0; q < NR; ++q) { s[q] = 0.f;
; #pragma unroll
;             for (int k = 0; k < 4; ++k) s[q] += v[q][k][0] * v[q][k][0] + v[q][k][1] * v[q][k][1] + v[q][k][2] * v[q][k][2] + v[q][k][3] * v[q][k][3]; }
; #pragma unroll
;         for (int o = 32; o > 0; o >>= 1)
; #pragma unroll
;             for (int q = 0; q < NR; ++q) s[q] += __shfl_xor(s[q], o);
	v_mov_b32_e32 v157, v69
	v_pk_fma_f32 v[150:151], v[150:151], v[150:151], v[152:153]
	v_mov_b32_e32 v152, v94
	v_mov_b32_e32 v153, v90
	v_pk_fma_f32 v[150:151], v[152:153], v[152:153], v[150:151]
	v_mov_b32_e32 v152, v95
	v_mov_b32_e32 v153, v91
	v_pk_fma_f32 v[170:171], v[152:153], v[152:153], v[150:151]
	v_mov_b32_e32 v152, v85
	v_mov_b32_e32 v153, v81
	v_mov_b32_e32 v150, v84
	v_mov_b32_e32 v151, v80
	v_pk_mul_f32 v[152:153], v[152:153], v[152:153]
	v_pk_mul_f32 v[156:157], v[156:157], v[156:157]
	v_pk_fma_f32 v[150:151], v[150:151], v[150:151], v[152:153]
	v_mov_b32_e32 v152, v86
	v_mov_b32_e32 v153, v82
	v_pk_fma_f32 v[150:151], v[152:153], v[152:153], v[150:151]
	v_mov_b32_e32 v152, v87
	v_mov_b32_e32 v153, v83
	v_pk_fma_f32 v[172:173], v[152:153], v[152:153], v[150:151]
	v_mov_b32_e32 v152, v77
	v_mov_b32_e32 v153, v57
	v_mov_b32_e32 v150, v76
	v_mov_b32_e32 v151, v56
	v_pk_mul_f32 v[152:153], v[152:153], v[152:153]
	s_waitcnt vmcnt(1)
	v_mov_b32_e32 v190, v65
	v_pk_fma_f32 v[150:151], v[150:151], v[150:151], v[152:153]
	v_mov_b32_e32 v152, v78
	v_mov_b32_e32 v153, v58
	v_pk_fma_f32 v[150:151], v[152:153], v[152:153], v[150:151]
	v_mov_b32_e32 v152, v79
	v_mov_b32_e32 v153, v59
	v_pk_fma_f32 v[158:159], v[152:153], v[152:153], v[150:151]
	v_mov_b32_e32 v152, v53
	v_mov_b32_e32 v153, v49
	v_mov_b32_e32 v150, v52
	v_mov_b32_e32 v151, v48
	v_pk_mul_f32 v[152:153], v[152:153], v[152:153]
	s_waitcnt vmcnt(0)
	v_mov_b32_e32 v191, v61
	v_pk_fma_f32 v[150:151], v[150:151], v[150:151], v[152:153]
	v_mov_b32_e32 v152, v54
	v_mov_b32_e32 v153, v50
	v_pk_fma_f32 v[150:151], v[152:153], v[152:153], v[150:151]
	v_mov_b32_e32 v152, v55
	v_mov_b32_e32 v153, v51
	v_pk_fma_f32 v[160:161], v[152:153], v[152:153], v[150:151]
	v_mov_b32_e32 v152, v45
	v_mov_b32_e32 v153, v41
	v_mov_b32_e32 v150, v44
	v_mov_b32_e32 v151, v40
	v_pk_mul_f32 v[152:153], v[152:153], v[152:153]
	v_pk_mul_f32 v[190:191], v[190:191], v[190:191]
	v_pk_fma_f32 v[150:151], v[150:151], v[150:151], v[152:153]
	v_mov_b32_e32 v152, v46
	v_mov_b32_e32 v153, v42
	v_pk_fma_f32 v[150:151], v[152:153], v[152:153], v[150:151]
	v_mov_b32_e32 v152, v47
	v_mov_b32_e32 v153, v43
	v_pk_fma_f32 v[162:163], v[152:153], v[152:153], v[150:151]
	v_mov_b32_e32 v152, v37
	v_mov_b32_e32 v153, v33
	v_mov_b32_e32 v150, v36
	v_mov_b32_e32 v151, v32
	v_pk_mul_f32 v[152:153], v[152:153], v[152:153]
	s_nop 0
	v_pk_fma_f32 v[150:151], v[150:151], v[150:151], v[152:153]
	v_mov_b32_e32 v152, v38
	v_mov_b32_e32 v153, v34
	v_pk_fma_f32 v[150:151], v[152:153], v[152:153], v[150:151]
	v_mov_b32_e32 v152, v39
	v_mov_b32_e32 v153, v35
	v_pk_fma_f32 v[164:165], v[152:153], v[152:153], v[150:151]
	v_mov_b32_e32 v152, v29
	v_mov_b32_e32 v153, v25
	v_mov_b32_e32 v150, v28
	v_mov_b32_e32 v151, v24
	v_pk_mul_f32 v[152:153], v[152:153], v[152:153]
	s_nop 0
	v_pk_fma_f32 v[150:151], v[150:151], v[150:151], v[152:153]
	v_mov_b32_e32 v152, v30
	v_mov_b32_e32 v153, v26
	v_pk_fma_f32 v[150:151], v[152:153], v[152:153], v[150:151]
	v_mov_b32_e32 v152, v31
	v_mov_b32_e32 v153, v27
	v_pk_fma_f32 v[150:151], v[152:153], v[152:153], v[150:151]
	v_mov_b32_e32 v152, v20
	v_mov_b32_e32 v153, v16
	v_pk_fma_f32 v[152:153], v[152:153], v[152:153], v[154:155]
	v_mov_b32_e32 v154, v22
	v_mov_b32_e32 v155, v18
	v_pk_fma_f32 v[152:153], v[154:155], v[154:155], v[152:153]
	v_mov_b32_e32 v154, v23
	v_mov_b32_e32 v155, v19
	v_pk_fma_f32 v[152:153], v[154:155], v[154:155], v[152:153]
	v_mov_b32_e32 v154, v72
	v_mov_b32_e32 v155, v68
	v_pk_fma_f32 v[154:155], v[154:155], v[154:155], v[156:157]
	v_mov_b32_e32 v156, v74
	v_mov_b32_e32 v157, v70
	v_pk_fma_f32 v[154:155], v[156:157], v[156:157], v[154:155]
	v_mov_b32_e32 v156, v75
	v_mov_b32_e32 v157, v71
	v_pk_fma_f32 v[154:155], v[156:157], v[156:157], v[154:155]
	v_mov_b32_e32 v156, v64
	v_mov_b32_e32 v157, v60
	v_pk_fma_f32 v[156:157], v[156:157], v[156:157], v[190:191]
	v_mov_b32_e32 v190, v66
	v_mov_b32_e32 v191, v62
	v_pk_fma_f32 v[156:157], v[190:191], v[190:191], v[156:157]
	v_mov_b32_e32 v190, v67
	v_mov_b32_e32 v191, v63
	v_pk_fma_f32 v[156:157], v[190:191], v[190:191], v[156:157]
	v_mov_b32_e32 v190, v186
	v_mov_b32_e32 v191, v174
	v_mov_b32_e32 v174, v187
	v_pk_add_f32 v[174:175], v[190:191], v[174:175]
	v_mov_b32_e32 v186, v188
	v_mov_b32_e32 v187, v176
	v_pk_add_f32 v[174:175], v[174:175], v[186:187]
	v_mov_b32_e32 v176, v189
	v_pk_add_f32 v[174:175], v[174:175], v[176:177]
	ds_bpermute_b32 v177, v178, v175
	ds_bpermute_b32 v176, v178, v174
	s_waitcnt lgkmcnt(0)
	v_pk_add_f32 v[174:175], v[174:175], v[176:177]
	ds_bpermute_b32 v177, v179, v175
	ds_bpermute_b32 v176, v179, v174
	s_waitcnt lgkmcnt(0)
	v_pk_add_f32 v[174:175], v[174:175], v[176:177]
	ds_bpermute_b32 v177, v180, v175
	ds_bpermute_b32 v176, v180, v174
	s_waitcnt lgkmcnt(0)
	v_pk_add_f32 v[174:175], v[174:175], v[176:177]
	ds_bpermute_b32 v177, v183, v175
	ds_bpermute_b32 v176, v183, v174
	s_waitcnt lgkmcnt(0)
	v_pk_add_f32 v[174:175], v[174:175], v[176:177]
	ds_bpermute_b32 v177, v184, v175
	ds_bpermute_b32 v176, v184, v174
	s_waitcnt lgkmcnt(0)
	v_pk_add_f32 v[174:175], v[174:175], v[176:177]
	ds_bpermute_b32 v177, v185, v175
	ds_bpermute_b32 v176, v185, v174
	s_waitcnt lgkmcnt(0)
; template <bool TO_BF16>
; DI void rms_rows(const int tid, const float* src, const float* gam, bf16_t* dst, float* fdst, int G, int c) {
;     ...
;             for (int q = 0; q < NR; ++q) s[q] += __shfl_xor(s[q], o);
; #pragma unroll
;         for (int q = 0; q < NR; ++q) { const float sc = rsqrtf(s[q] * (1.f / 1024.f) + 1e-6f);
; #pragma unroll
;             for (int k = 0; k < 4; ++k) {
;                 if (TO_BF16) { u32x2 o; o.x = pk2(v[q][k][0] * sc * g4[k][0], v[q][k][1] * sc * g4[k][1]); o.y = pk2(v[q][k][2] * sc * g4[k][2], v[q][k][3] * sc * g4[k][3]);
;                     *(u32x2*)(dst + (size_t)(r + q) * 1024 + k * 256 + lane * 4) = o; }
;                 else *(f32x4*)(fdst + (size_t)(r + q) * 1024 + k * 256 + lane * 4) = v[q][k] * sc * g4[k]; } }
	v_pk_add_f32 v[176:177], v[174:175], v[176:177]
	v_mov_b64_e32 v[174:175], s[14:15]
	v_pk_fma_f32 v[176:177], v[176:177], s[2:3], v[174:175] op_sel_hi:[1,0,0]
	s_nop 0
	v_mul_f32_e32 v145, 0x4b800000, v177
	v_cmp_gt_f32_e64 s[0:1], s3, v177
	v_cmp_gt_f32_e32 vcc, s3, v176
	s_nop 0
	v_cndmask_b32_e64 v145, v177, v145, s[0:1]
	v_rsq_f32_e32 v145, v145
	s_nop 0
	v_mul_f32_e32 v177, 0x45800000, v145
	v_cndmask_b32_e64 v186, v145, v177, s[0:1]
	v_pk_mul_f32 v[140:141], v[140:141], v[186:187] op_sel_hi:[1,0]
	v_pk_mul_f32 v[142:143], v[142:143], v[186:187] op_sel_hi:[1,0]
	v_pk_mul_f32 v[140:141], v[12:13], v[140:141]
	v_pk_mul_f32 v[142:143], v[14:15], v[142:143]
	v_pk_mul_f32 v[128:129], v[128:129], v[186:187] op_sel_hi:[1,0]
	v_pk_mul_f32 v[130:131], v[130:131], v[186:187] op_sel_hi:[1,0]
	v_cvt_pk_bf16_f32 v140, v140, v141
	v_cvt_pk_bf16_f32 v141, v142, v143
	v_add_co_u32_e64 v142, s[0:1], s10, v146
	v_pk_mul_f32 v[128:129], v[0:1], v[128:129]
	v_pk_mul_f32 v[130:131], v[2:3], v[130:131]
	v_addc_co_u32_e64 v143, s[0:1], -1, v147, s[0:1]
	v_cvt_pk_bf16_f32 v128, v128, v129
	v_cvt_pk_bf16_f32 v129, v130, v131
	global_store_dwordx2 v[142:143], v[128:129], off offset:-2048
	v_mul_f32_e32 v128, 0x4b800000, v176
	v_cndmask_b32_e32 v128, v176, v128, vcc
	v_rsq_f32_e32 v128, v128
	v_pk_mul_f32 v[136:137], v[136:137], v[186:187] op_sel_hi:[1,0]
	v_pk_mul_f32 v[138:139], v[138:139], v[186:187] op_sel_hi:[1,0]
	v_pk_mul_f32 v[132:133], v[132:133], v[186:187] op_sel_hi:[1,0]
	v_mul_f32_e32 v129, 0x45800000, v128
	v_cndmask_b32_e32 v128, v128, v129, vcc
	v_pk_mul_f32 v[112:113], v[112:113], v[128:129] op_sel_hi:[1,0]
	v_pk_mul_f32 v[114:115], v[114:115], v[128:129] op_sel_hi:[1,0]
	v_pk_mul_f32 v[112:113], v[0:1], v[112:113]
	v_pk_mul_f32 v[114:115], v[2:3], v[114:115]
	v_pk_mul_f32 v[116:117], v[116:117], v[128:129] op_sel_hi:[1,0]
	v_pk_mul_f32 v[118:119], v[118:119], v[128:129] op_sel_hi:[1,0]
	v_cvt_pk_bf16_f32 v112, v112, v113
	v_cvt_pk_bf16_f32 v113, v114, v115
	v_add_co_u32_e32 v114, vcc, s11, v146
	v_pk_mul_f32 v[116:117], v[4:5], v[116:117]
	v_pk_mul_f32 v[118:119], v[6:7], v[118:119]
	v_addc_co_u32_e32 v115, vcc, -1, v147, vcc
	v_cvt_pk_bf16_f32 v116, v116, v117
	v_cvt_pk_bf16_f32 v117, v118, v119
	global_store_dwordx2 v[114:115], v[112:113], off offset:-4096
	v_mov_b32_e32 v112, v170
	v_mov_b32_e32 v113, v166
	v_mov_b32_e32 v166, v171
	global_store_dwordx2 v[142:143], v[116:117], off offset:-512
	v_pk_add_f32 v[112:113], v[112:113], v[166:167]
	v_mov_b32_e32 v116, v172
	v_mov_b32_e32 v117, v168
	v_pk_add_f32 v[112:113], v[112:113], v[116:117]
	v_mov_b32_e32 v168, v173
	v_pk_add_f32 v[112:113], v[112:113], v[168:169]
	ds_bpermute_b32 v117, v178, v113
	ds_bpermute_b32 v116, v178, v112
	v_pk_mul_f32 v[134:135], v[134:135], v[186:187] op_sel_hi:[1,0]
	v_pk_mul_f32 v[124:125], v[124:125], v[128:129] op_sel_hi:[1,0]
	v_pk_mul_f32 v[126:127], v[126:127], v[128:129] op_sel_hi:[1,0]
	v_pk_mul_f32 v[120:121], v[120:121], v[128:129] op_sel_hi:[1,0]
	s_waitcnt lgkmcnt(0)
	v_pk_add_f32 v[112:113], v[112:113], v[116:117]
	ds_bpermute_b32 v117, v179, v113
	ds_bpermute_b32 v116, v179, v112
	v_pk_mul_f32 v[122:123], v[122:123], v[128:129] op_sel_hi:[1,0]
	v_pk_mul_f32 v[136:137], v[8:9], v[136:137]
	v_pk_mul_f32 v[138:139], v[10:11], v[138:139]
	v_pk_mul_f32 v[132:133], v[4:5], v[132:133]
	s_waitcnt lgkmcnt(0)
	v_pk_add_f32 v[112:113], v[112:113], v[116:117]
	ds_bpermute_b32 v117, v180, v113
	ds_bpermute_b32 v116, v180, v112
	v_pk_mul_f32 v[134:135], v[6:7], v[134:135]
	v_pk_mul_f32 v[124:125], v[12:13], v[124:125]
	v_pk_mul_f32 v[126:127], v[14:15], v[126:127]
	v_pk_mul_f32 v[120:121], v[8:9], v[120:121]
	s_waitcnt lgkmcnt(0)
	v_pk_add_f32 v[112:113], v[112:113], v[116:117]
	ds_bpermute_b32 v117, v183, v113
	ds_bpermute_b32 v116, v183, v112
	v_pk_mul_f32 v[122:123], v[10:11], v[122:123]
	v_cvt_pk_bf16_f32 v136, v136, v137
	v_cvt_pk_bf16_f32 v137, v138, v139
	v_cvt_pk_bf16_f32 v132, v132, v133
	s_waitcnt lgkmcnt(0)
	v_pk_add_f32 v[112:113], v[112:113], v[116:117]
	ds_bpermute_b32 v117, v184, v113
	ds_bpermute_b32 v116, v184, v112
	v_cvt_pk_bf16_f32 v133, v134, v135
	v_cvt_pk_bf16_f32 v124, v124, v125
	v_cvt_pk_bf16_f32 v125, v126, v127
	v_cvt_pk_bf16_f32 v120, v120, v121
	s_waitcnt lgkmcnt(0)
	v_pk_add_f32 v[112:113], v[112:113], v[116:117]
	ds_bpermute_b32 v117, v185, v113
	ds_bpermute_b32 v116, v185, v112
	v_cvt_pk_bf16_f32 v121, v122, v123
	global_store_dwordx2 v[142:143], v[140:141], off offset:-3584
	global_store_dwordx2 v[142:143], v[136:137], off offset:-3072
	global_store_dwordx2 v[142:143], v[132:133], off offset:-2560
	s_waitcnt lgkmcnt(0)
; template <bool TO_BF16>
; DI void rms_rows(const int tid, const float* src, const float* gam, bf16_t* dst, float* fdst, int G, int c) {
;     ...
;             for (int q = 0; q < NR; ++q) s[q] += __shfl_xor(s[q], o);
; #pragma unroll
;         for (int q = 0; q < NR; ++q) { const float sc = rsqrtf(s[q] * (1.f / 1024.f) + 1e-6f);
; #pragma unroll
;             for (int k = 0; k < 4; ++k) {
;                 if (TO_BF16) { u32x2 o; o.x = pk2(v[q][k][0] * sc * g4[k][0], v[q][k][1] * sc * g4[k][1]); o.y = pk2(v[q][k][2] * sc * g4[k][2], v[q][k][3] * sc * g4[k][3]);
;                     *(u32x2*)(dst + (size_t)(r + q) * 1024 + k * 256 + lane * 4) = o; }
;                 else *(f32x4*)(fdst + (size_t)(r + q) * 1024 + k * 256 + lane * 4) = v[q][k] * sc * g4[k]; } }
	v_pk_add_f32 v[112:113], v[112:113], v[116:117]
	global_store_dwordx2 v[142:143], v[124:125], off offset:-1536
	v_pk_fma_f32 v[112:113], v[112:113], s[2:3], v[174:175] op_sel_hi:[1,0,0]
	global_store_dwordx2 v[142:143], v[120:121], off offset:-1024
	v_mul_f32_e32 v116, 0x4b800000, v113
	v_cmp_gt_f32_e64 s[0:1], s3, v113
	v_cmp_gt_f32_e32 vcc, s3, v112
	s_nop 0
	v_cndmask_b32_e64 v113, v113, v116, s[0:1]
	v_rsq_f32_e32 v113, v113
	s_nop 0
	v_mul_f32_e32 v116, 0x45800000, v113
	v_cndmask_b32_e64 v116, v113, v116, s[0:1]
	v_pk_mul_f32 v[96:97], v[96:97], v[116:117] op_sel_hi:[1,0]
	v_pk_mul_f32 v[98:99], v[98:99], v[116:117] op_sel_hi:[1,0]
	v_pk_mul_f32 v[96:97], v[0:1], v[96:97]
	v_pk_mul_f32 v[98:99], v[2:3], v[98:99]
	v_cvt_pk_bf16_f32 v96, v96, v97
	v_cvt_pk_bf16_f32 v97, v98, v99
	global_store_dwordx2 v[114:115], v[96:97], off offset:-2048
	v_mul_f32_e32 v96, 0x4b800000, v112
	v_cndmask_b32_e32 v96, v112, v96, vcc
	v_rsq_f32_e32 v96, v96
	v_pk_mul_f32 v[108:109], v[108:109], v[116:117] op_sel_hi:[1,0]
	v_pk_mul_f32 v[110:111], v[110:111], v[116:117] op_sel_hi:[1,0]
	v_pk_mul_f32 v[104:105], v[104:105], v[116:117] op_sel_hi:[1,0]
	v_mul_f32_e32 v97, 0x45800000, v96
	v_cndmask_b32_e32 v96, v96, v97, vcc
	v_pk_mul_f32 v[80:81], v[80:81], v[96:97] op_sel_hi:[1,0]
	v_pk_mul_f32 v[82:83], v[82:83], v[96:97] op_sel_hi:[1,0]
	v_pk_mul_f32 v[80:81], v[0:1], v[80:81]
	v_pk_mul_f32 v[82:83], v[2:3], v[82:83]
	v_cvt_pk_bf16_f32 v80, v80, v81
	v_cvt_pk_bf16_f32 v81, v82, v83
	global_store_dwordx2 v[114:115], v[80:81], off
	v_mov_b32_e32 v80, v162
	v_mov_b32_e32 v81, v158
	v_mov_b32_e32 v158, v163
	v_pk_add_f32 v[80:81], v[80:81], v[158:159]
	v_mov_b32_e32 v82, v164
	v_mov_b32_e32 v83, v160
	v_pk_add_f32 v[80:81], v[80:81], v[82:83]
	v_mov_b32_e32 v160, v165
	v_pk_add_f32 v[80:81], v[80:81], v[160:161]
	ds_bpermute_b32 v83, v178, v81
	ds_bpermute_b32 v82, v178, v80
	v_pk_mul_f32 v[106:107], v[106:107], v[116:117] op_sel_hi:[1,0]
	v_pk_mul_f32 v[100:101], v[100:101], v[116:117] op_sel_hi:[1,0]
	v_pk_mul_f32 v[102:103], v[102:103], v[116:117] op_sel_hi:[1,0]
	v_pk_mul_f32 v[92:93], v[92:93], v[96:97] op_sel_hi:[1,0]
	s_waitcnt lgkmcnt(0)
	v_pk_add_f32 v[80:81], v[80:81], v[82:83]
	ds_bpermute_b32 v83, v179, v81
	ds_bpermute_b32 v82, v179, v80
	v_pk_mul_f32 v[94:95], v[94:95], v[96:97] op_sel_hi:[1,0]
	v_pk_mul_f32 v[88:89], v[88:89], v[96:97] op_sel_hi:[1,0]
	v_pk_mul_f32 v[90:91], v[90:91], v[96:97] op_sel_hi:[1,0]
	v_pk_mul_f32 v[84:85], v[84:85], v[96:97] op_sel_hi:[1,0]
	s_waitcnt lgkmcnt(0)
	v_pk_add_f32 v[80:81], v[80:81], v[82:83]
	ds_bpermute_b32 v83, v180, v81
	ds_bpermute_b32 v82, v180, v80
	v_pk_mul_f32 v[86:87], v[86:87], v[96:97] op_sel_hi:[1,0]
	v_pk_mul_f32 v[108:109], v[12:13], v[108:109]
	v_pk_mul_f32 v[110:111], v[14:15], v[110:111]
	v_pk_mul_f32 v[104:105], v[8:9], v[104:105]
	s_waitcnt lgkmcnt(0)
	v_pk_add_f32 v[80:81], v[80:81], v[82:83]
	ds_bpermute_b32 v83, v183, v81
	ds_bpermute_b32 v82, v183, v80
	v_pk_mul_f32 v[106:107], v[10:11], v[106:107]
	v_pk_mul_f32 v[100:101], v[4:5], v[100:101]
	v_pk_mul_f32 v[102:103], v[6:7], v[102:103]
	v_pk_mul_f32 v[92:93], v[12:13], v[92:93]
	s_waitcnt lgkmcnt(0)
	v_pk_add_f32 v[80:81], v[80:81], v[82:83]
	ds_bpermute_b32 v83, v184, v81
	ds_bpermute_b32 v82, v184, v80
	v_pk_mul_f32 v[94:95], v[14:15], v[94:95]
	v_pk_mul_f32 v[88:89], v[8:9], v[88:89]
	v_pk_mul_f32 v[90:91], v[10:11], v[90:91]
	v_pk_mul_f32 v[84:85], v[4:5], v[84:85]
	s_waitcnt lgkmcnt(0)
	v_pk_add_f32 v[80:81], v[80:81], v[82:83]
	ds_bpermute_b32 v83, v185, v81
	ds_bpermute_b32 v82, v185, v80
	v_pk_mul_f32 v[86:87], v[6:7], v[86:87]
	v_cvt_pk_bf16_f32 v108, v108, v109
	v_cvt_pk_bf16_f32 v109, v110, v111
	v_cvt_pk_bf16_f32 v104, v104, v105
	s_waitcnt lgkmcnt(0)
	v_pk_add_f32 v[80:81], v[80:81], v[82:83]
	v_cvt_pk_bf16_f32 v105, v106, v107
	v_pk_fma_f32 v[80:81], v[80:81], s[2:3], v[174:175] op_sel_hi:[1,0,0]
	v_cvt_pk_bf16_f32 v100, v100, v101
	v_mul_f32_e32 v82, 0x4b800000, v81
	v_cmp_gt_f32_e64 s[0:1], s3, v81
	v_cmp_gt_f32_e32 vcc, s3, v80
	v_cvt_pk_bf16_f32 v101, v102, v103
	v_cndmask_b32_e64 v81, v81, v82, s[0:1]
	v_rsq_f32_e32 v81, v81
	v_cvt_pk_bf16_f32 v92, v92, v93
	v_cvt_pk_bf16_f32 v93, v94, v95
	v_cvt_pk_bf16_f32 v88, v88, v89
	v_mul_f32_e32 v82, 0x45800000, v81
	v_cndmask_b32_e64 v82, v81, v82, s[0:1]
	v_pk_mul_f32 v[76:77], v[76:77], v[82:83] op_sel_hi:[1,0]
	v_pk_mul_f32 v[78:79], v[78:79], v[82:83] op_sel_hi:[1,0]
	v_pk_mul_f32 v[76:77], v[12:13], v[76:77]
	v_pk_mul_f32 v[78:79], v[14:15], v[78:79]
	v_pk_mul_f32 v[48:49], v[48:49], v[82:83] op_sel_hi:[1,0]
	v_pk_mul_f32 v[50:51], v[50:51], v[82:83] op_sel_hi:[1,0]
	v_cvt_pk_bf16_f32 v76, v76, v77
	v_cvt_pk_bf16_f32 v77, v78, v79
	v_add_co_u32_e64 v78, s[0:1], s12, v146
	v_pk_mul_f32 v[48:49], v[0:1], v[48:49]
	v_pk_mul_f32 v[50:51], v[2:3], v[50:51]
	v_addc_co_u32_e64 v79, s[0:1], -1, v147, s[0:1]
	v_cvt_pk_bf16_f32 v48, v48, v49
	v_cvt_pk_bf16_f32 v49, v50, v51
	global_store_dwordx2 v[78:79], v[48:49], off offset:-2048
	v_mul_f32_e32 v48, 0x4b800000, v80
	v_cndmask_b32_e32 v48, v80, v48, vcc
	v_rsq_f32_e32 v48, v48
	v_pk_mul_f32 v[56:57], v[56:57], v[82:83] op_sel_hi:[1,0]
	v_pk_mul_f32 v[58:59], v[58:59], v[82:83] op_sel_hi:[1,0]
	v_pk_mul_f32 v[52:53], v[52:53], v[82:83] op_sel_hi:[1,0]
	v_mul_f32_e32 v49, 0x45800000, v48
	v_cndmask_b32_e32 v48, v48, v49, vcc
	v_pk_mul_f32 v[32:33], v[32:33], v[48:49] op_sel_hi:[1,0]
	v_pk_mul_f32 v[34:35], v[34:35], v[48:49] op_sel_hi:[1,0]
	v_pk_mul_f32 v[32:33], v[0:1], v[32:33]
	v_pk_mul_f32 v[34:35], v[2:3], v[34:35]
	v_cvt_pk_bf16_f32 v32, v32, v33
	v_cvt_pk_bf16_f32 v33, v34, v35
	global_store_dwordx2 v[146:147], v[32:33], off offset:-4096
	v_mov_b32_e32 v32, v154
	v_mov_b32_e32 v33, v150
	v_mov_b32_e32 v150, v155
	v_pk_add_f32 v[32:33], v[32:33], v[150:151]
	v_mov_b32_e32 v34, v156
	v_mov_b32_e32 v35, v152
	v_pk_add_f32 v[32:33], v[32:33], v[34:35]
	v_mov_b32_e32 v152, v157
	v_pk_add_f32 v[32:33], v[32:33], v[152:153]
	ds_bpermute_b32 v35, v178, v33
	ds_bpermute_b32 v34, v178, v32
	v_pk_mul_f32 v[54:55], v[54:55], v[82:83] op_sel_hi:[1,0]
	v_pk_mul_f32 v[44:45], v[44:45], v[48:49] op_sel_hi:[1,0]
	v_pk_mul_f32 v[46:47], v[46:47], v[48:49] op_sel_hi:[1,0]
	v_pk_mul_f32 v[40:41], v[40:41], v[48:49] op_sel_hi:[1,0]
	s_waitcnt lgkmcnt(0)
; template <bool TO_BF16>
; DI void rms_rows(const int tid, const float* src, const float* gam, bf16_t* dst, float* fdst, int G, int c) {
;     ...
;             for (int q = 0; q < NR; ++q) s[q] += __shfl_xor(s[q], o);
; #pragma unroll
;         for (int q = 0; q < NR; ++q) { const float sc = rsqrtf(s[q] * (1.f / 1024.f) + 1e-6f);
; #pragma unroll
;             for (int k = 0; k < 4; ++k) {
;                 if (TO_BF16) { u32x2 o; o.x = pk2(v[q][k][0] * sc * g4[k][0], v[q][k][1] * sc * g4[k][1]); o.y = pk2(v[q][k][2] * sc * g4[k][2], v[q][k][3] * sc * g4[k][3]);
;                     *(u32x2*)(dst + (size_t)(r + q) * 1024 + k * 256 + lane * 4) = o; }
;                 else *(f32x4*)(fdst + (size_t)(r + q) * 1024 + k * 256 + lane * 4) = v[q][k] * sc * g4[k]; } }
	v_pk_add_f32 v[32:33], v[32:33], v[34:35]
	ds_bpermute_b32 v35, v179, v33
	ds_bpermute_b32 v34, v179, v32
	v_pk_mul_f32 v[42:43], v[42:43], v[48:49] op_sel_hi:[1,0]
	v_pk_mul_f32 v[36:37], v[36:37], v[48:49] op_sel_hi:[1,0]
	v_pk_mul_f32 v[38:39], v[38:39], v[48:49] op_sel_hi:[1,0]
	v_pk_mul_f32 v[56:57], v[8:9], v[56:57]
	s_waitcnt lgkmcnt(0)
	v_pk_add_f32 v[32:33], v[32:33], v[34:35]
	ds_bpermute_b32 v35, v180, v33
	ds_bpermute_b32 v34, v180, v32
	v_pk_mul_f32 v[58:59], v[10:11], v[58:59]
	v_pk_mul_f32 v[52:53], v[4:5], v[52:53]
	v_pk_mul_f32 v[54:55], v[6:7], v[54:55]
	v_pk_mul_f32 v[44:45], v[12:13], v[44:45]
	s_waitcnt lgkmcnt(0)
	v_pk_add_f32 v[32:33], v[32:33], v[34:35]
	ds_bpermute_b32 v35, v183, v33
	ds_bpermute_b32 v34, v183, v32
	v_pk_mul_f32 v[46:47], v[14:15], v[46:47]
	v_pk_mul_f32 v[40:41], v[8:9], v[40:41]
	v_pk_mul_f32 v[42:43], v[10:11], v[42:43]
	v_pk_mul_f32 v[36:37], v[4:5], v[36:37]
	s_waitcnt lgkmcnt(0)
	v_pk_add_f32 v[32:33], v[32:33], v[34:35]
	ds_bpermute_b32 v35, v184, v33
	ds_bpermute_b32 v34, v184, v32
	v_pk_mul_f32 v[38:39], v[6:7], v[38:39]
	v_cvt_pk_bf16_f32 v89, v90, v91
	v_cvt_pk_bf16_f32 v84, v84, v85
	v_cvt_pk_bf16_f32 v85, v86, v87
	s_waitcnt lgkmcnt(0)
	v_pk_add_f32 v[32:33], v[32:33], v[34:35]
	ds_bpermute_b32 v35, v185, v33
	ds_bpermute_b32 v34, v185, v32
	v_cvt_pk_bf16_f32 v56, v56, v57
	v_cvt_pk_bf16_f32 v57, v58, v59
	v_cvt_pk_bf16_f32 v52, v52, v53
	v_cvt_pk_bf16_f32 v53, v54, v55
	s_waitcnt lgkmcnt(0)
	v_pk_add_f32 v[32:33], v[32:33], v[34:35]
	v_cvt_pk_bf16_f32 v44, v44, v45
	v_pk_fma_f32 v[32:33], v[32:33], s[2:3], v[174:175] op_sel_hi:[1,0,0]
	v_cvt_pk_bf16_f32 v45, v46, v47
	v_mul_f32_e32 v34, 0x4b800000, v33
	v_cmp_gt_f32_e64 s[0:1], s3, v33
	v_cmp_gt_f32_e32 vcc, s3, v32
	v_cvt_pk_bf16_f32 v40, v40, v41
	v_cndmask_b32_e64 v33, v33, v34, s[0:1]
	v_rsq_f32_e32 v33, v33
	v_cvt_pk_bf16_f32 v41, v42, v43
	v_cvt_pk_bf16_f32 v36, v36, v37
	v_cvt_pk_bf16_f32 v37, v38, v39
	v_mul_f32_e32 v34, 0x45800000, v33
	v_cndmask_b32_e64 v34, v33, v34, s[0:1]
	v_pk_mul_f32 v[16:17], v[16:17], v[34:35] op_sel_hi:[1,0]
	v_pk_mul_f32 v[18:19], v[18:19], v[34:35] op_sel_hi:[1,0]
	v_pk_mul_f32 v[16:17], v[0:1], v[16:17]
	v_pk_mul_f32 v[18:19], v[2:3], v[18:19]
	v_cvt_pk_bf16_f32 v16, v16, v17
	v_cvt_pk_bf16_f32 v17, v18, v19
	global_store_dwordx2 v[146:147], v[16:17], off offset:-2048
	v_mul_f32_e32 v16, 0x4b800000, v32
	v_cndmask_b32_e32 v16, v32, v16, vcc
	v_rsq_f32_e32 v16, v16
	v_pk_mul_f32 v[20:21], v[20:21], v[34:35] op_sel_hi:[1,0]
	v_pk_mul_f32 v[22:23], v[22:23], v[34:35] op_sel_hi:[1,0]
	v_pk_mul_f32 v[20:21], v[4:5], v[20:21]
	v_pk_mul_f32 v[22:23], v[6:7], v[22:23]
	v_mul_f32_e32 v17, 0x45800000, v16
	v_cvt_pk_bf16_f32 v20, v20, v21
	v_cvt_pk_bf16_f32 v21, v22, v23
	v_cndmask_b32_e32 v16, v16, v17, vcc
	global_store_dwordx2 v[146:147], v[20:21], off offset:-2560
	v_pk_mul_f32 v[18:19], v[72:73], v[16:17] op_sel_hi:[1,0]
	v_pk_mul_f32 v[20:21], v[74:75], v[16:17] op_sel_hi:[1,0]
	v_pk_mul_f32 v[18:19], v[12:13], v[18:19]
	v_pk_mul_f32 v[20:21], v[14:15], v[20:21]
	v_cvt_pk_bf16_f32 v18, v18, v19
	v_cvt_pk_bf16_f32 v19, v20, v21
	global_store_dwordx2 v[146:147], v[18:19], off offset:-1536
	v_pk_mul_f32 v[18:19], v[68:69], v[16:17] op_sel_hi:[1,0]
	v_pk_mul_f32 v[20:21], v[70:71], v[16:17] op_sel_hi:[1,0]
	v_pk_mul_f32 v[18:19], v[8:9], v[18:19]
	v_pk_mul_f32 v[20:21], v[10:11], v[20:21]
	v_cvt_pk_bf16_f32 v18, v18, v19
	v_cvt_pk_bf16_f32 v19, v20, v21
	global_store_dwordx2 v[146:147], v[18:19], off offset:-1024
	v_pk_mul_f32 v[18:19], v[64:65], v[16:17] op_sel_hi:[1,0]
	v_pk_mul_f32 v[20:21], v[66:67], v[16:17] op_sel_hi:[1,0]
	v_pk_mul_f32 v[18:19], v[4:5], v[18:19]
	v_pk_mul_f32 v[20:21], v[6:7], v[20:21]
	v_cvt_pk_bf16_f32 v18, v18, v19
	v_cvt_pk_bf16_f32 v19, v20, v21
	v_pk_mul_f32 v[28:29], v[28:29], v[34:35] op_sel_hi:[1,0]
	v_pk_mul_f32 v[30:31], v[30:31], v[34:35] op_sel_hi:[1,0]
	v_pk_mul_f32 v[24:25], v[24:25], v[34:35] op_sel_hi:[1,0]
	v_pk_mul_f32 v[26:27], v[26:27], v[34:35] op_sel_hi:[1,0]
	global_store_dwordx2 v[146:147], v[18:19], off offset:-512
	v_pk_mul_f32 v[18:19], v[60:61], v[16:17] op_sel_hi:[1,0]
	v_pk_mul_f32 v[16:17], v[62:63], v[16:17] op_sel_hi:[1,0]
	v_pk_mul_f32 v[28:29], v[12:13], v[28:29]
	v_pk_mul_f32 v[30:31], v[14:15], v[30:31]
	v_pk_mul_f32 v[24:25], v[8:9], v[24:25]
	v_pk_mul_f32 v[26:27], v[10:11], v[26:27]
	v_pk_mul_f32 v[18:19], v[0:1], v[18:19]
	v_pk_mul_f32 v[16:17], v[2:3], v[16:17]
	v_cvt_pk_bf16_f32 v28, v28, v29
	v_cvt_pk_bf16_f32 v29, v30, v31
	v_cvt_pk_bf16_f32 v24, v24, v25
	v_cvt_pk_bf16_f32 v25, v26, v27
	v_cvt_pk_bf16_f32 v18, v18, v19
	v_cvt_pk_bf16_f32 v19, v16, v17
	v_cmp_lt_i32_e32 vcc, s70, v144
	global_store_dwordx2 v[146:147], v[28:29], off offset:-3584
	global_store_dwordx2 v[146:147], v[24:25], off offset:-3072
	global_store_dwordx2 v[146:147], v[18:19], off
	v_lshl_add_u64 v[146:147], v[146:147], 0, s[8:9]
	s_or_b64 s[6:7], vcc, s[6:7]
	global_store_dwordx2 v[114:115], v[108:109], off offset:-3584
	global_store_dwordx2 v[114:115], v[104:105], off offset:-3072
	global_store_dwordx2 v[114:115], v[100:101], off offset:-2560
	global_store_dwordx2 v[114:115], v[92:93], off offset:-1536
	global_store_dwordx2 v[114:115], v[88:89], off offset:-1024
	global_store_dwordx2 v[114:115], v[84:85], off offset:-512
	global_store_dwordx2 v[78:79], v[76:77], off offset:-3584
	global_store_dwordx2 v[78:79], v[56:57], off offset:-3072
	global_store_dwordx2 v[78:79], v[52:53], off offset:-2560
	global_store_dwordx2 v[78:79], v[44:45], off offset:-1536
	global_store_dwordx2 v[78:79], v[40:41], off offset:-1024
	global_store_dwordx2 v[78:79], v[36:37], off offset:-512
	s_andn2_b64 exec, exec, s[6:7]
	s_cbranch_execnz .LBB0_394
